# U sweep: softmax gate fetched once per four steps directly for the lane's batched expert (no per-step gate read/select)
# baseline (speedup 1.0000x reference)
; __device__ __forceinline__ float key2f(unsigned k) { return __uint_as_float((k & 0x80000000u) ? (k & 0x7fffffffu) : ~k); }
; __device__ void ph_peer(const float* __restrict__ SC, const bf16_t* __restrict__ H  , const float* __restrict__ gffn, const unsigned char* __restrict__ U, const unsigned char* __restrict__ V, float* X, const float* __restrict__ fgain) {
;     ...
;             for (int u = 0; u < 2; ++u) {
;                 const float bs = key2f(best[u] & ~255u);
;                 const int pos = 255 - (int)(best[u] & 255u);
;                 const int e0 = __shfl(n0[u], (pos >> 4) & 15), e1 = __shfl(n1[u], pos & 15);
;                 const float mxs = __shfl(bs, 0);
;                 float e = lane < 16 ? __expf((bs - mxs) * rstd) : 0.f;
;                 const float den = row16_sum(e);
;                 const int iv = __shfl(e0 * 128 + e1, lane & 15); const float gv = __shfl(e / den, lane & 15);
;                 const int hh = h + u;
;                 if (grp == (hh & 3)) { if (hh < 4) { idx_lo = iv; g_lo = gv; } else { idx_hi = iv; g_hi = gv; } } }
.Lpeer_partB_b:
	v_lshrrev_b32_e32 v2, 11, v72
	v_lshrrev_b32_e32 v3, 6, v131
	v_lshl_add_u32 v2, v2, 3, v91
	v_mul_u32_u24_e32 v3, 0x1c00, v3
	v_mul_u32_u24_e32 v2, 0x70, v2
	v_and_b32_e32 v4, 15, v74
	v_add_u32_e32 v3, 0x12000, v3
	v_add_u32_e32 v2, v3, v2
	v_add_u32_e32 v5, v2, v4
	v_lshl_add_u32 v6, v4, 2, v2
	ds_read_u8 v7, v5 offset:96
	ds_read_u8 v8, v5 offset:544
	ds_read_b32 v9, v6 offset:32
	ds_read_b32 v10, v6 offset:480
	ds_read_b32 v11, v2 offset:32
	ds_read_b32 v13, v2 offset:480
	s_waitcnt lgkmcnt(4)
	v_not_b32_e32 v7, v7
	v_not_b32_e32 v8, v8
	v_bfe_u32 v14, v7, 4, 4
	v_and_b32_e32 v7, 15, v7
	v_bfe_u32 v15, v8, 4, 4
	v_and_b32_e32 v8, 15, v8
	v_add_u32_e32 v14, v2, v14
	v_add_u32_e32 v7, v2, v7
	v_add_u32_e32 v15, v2, v15
	v_add_u32_e32 v8, v2, v8
	ds_read_u8 v14, v14
	ds_read_u8 v7, v7 offset:16
	ds_read_u8 v15, v15 offset:448
	ds_read_u8 v8, v8 offset:464
	s_waitcnt lgkmcnt(4)
	v_sub_f32_e32 v9, v9, v11
	v_sub_f32_e32 v10, v10, v13
	v_mul_f32_e32 v9, v12, v9
	v_mul_f32_e32 v10, v12, v10
	v_mul_f32_e32 v9, 0x3fb8aa3b, v9
	v_mul_f32_e32 v10, 0x3fb8aa3b, v10
	v_exp_f32_e32 v9, v9
	v_exp_f32_e32 v10, v10
	s_nop 1
	v_add_f32_dpp v11, v9, v9 quad_perm:[1,0,3,2] row_mask:0xf bank_mask:0xf bound_ctrl:1
	v_add_f32_dpp v13, v10, v10 quad_perm:[1,0,3,2] row_mask:0xf bank_mask:0xf bound_ctrl:1
	s_nop 0
	v_add_f32_dpp v11, v11, v11 quad_perm:[2,3,0,1] row_mask:0xf bank_mask:0xf bound_ctrl:1
	v_add_f32_dpp v13, v13, v13 quad_perm:[2,3,0,1] row_mask:0xf bank_mask:0xf bound_ctrl:1
	s_nop 0
	v_add_f32_dpp v11, v11, v11 row_half_mirror row_mask:0xf bank_mask:0xf bound_ctrl:1
	v_add_f32_dpp v13, v13, v13 row_half_mirror row_mask:0xf bank_mask:0xf bound_ctrl:1
	s_nop 0
	v_add_f32_dpp v11, v11, v11 row_mirror row_mask:0xf bank_mask:0xf bound_ctrl:1
	v_add_f32_dpp v13, v13, v13 row_mirror row_mask:0xf bank_mask:0xf bound_ctrl:1
	s_nop 0
	v_div_scale_f32 v16, s[0:1], v11, v11, v9
	v_div_scale_f32 v17, s[0:1], v13, v13, v10
	v_rcp_f32_e32 v18, v16
	v_rcp_f32_e32 v19, v17
	s_nop 0
	v_fma_f32 v20, -v16, v18, 1.0
	v_fma_f32 v21, -v17, v19, 1.0
	v_fmac_f32_e32 v18, v20, v18
	v_fmac_f32_e32 v19, v21, v19
	v_div_scale_f32 v20, vcc, v9, v11, v9
	v_mul_f32_e32 v22, v20, v18
	v_fma_f32 v24, -v16, v22, v20
	v_fmac_f32_e32 v22, v24, v18
	v_fma_f32 v20, -v16, v22, v20
	v_div_fmas_f32 v20, v20, v18, v22
	v_div_fixup_f32 v73, v20, v11, v9
	v_div_scale_f32 v21, vcc, v10, v13, v10
	v_mul_f32_e32 v23, v21, v19
	v_fma_f32 v25, -v17, v23, v21
	v_fmac_f32_e32 v23, v25, v19
	v_fma_f32 v21, -v17, v23, v21
	v_div_fmas_f32 v21, v21, v19, v23
	v_div_fixup_f32 v158, v21, v13, v10
	s_waitcnt lgkmcnt(0)
	v_and_b32_e32 v14, 0x7f, v14
	v_and_b32_e32 v7, 0x7f, v7
	v_and_b32_e32 v15, 0x7f, v15
	v_and_b32_e32 v8, 0x7f, v8
	v_lshl_or_b32 v14, v14, 7, v7
	v_lshl_or_b32 v15, v15, 7, v8
	v_xor_b32_e32 v156, 0x3fff, v14
	v_xor_b32_e32 v157, 0x3fff, v15
	v_lshrrev_b32_e32 v2, 11, v156
	v_lshrrev_b32_e32 v3, 11, v157
	s_mov_b32 s2, 0
	v_mov_b32_e32 v6, 0
	v_mov_b32_e32 v7, 0
	v_cmp_eq_u32_e64 s[0:1], 0, v2
	v_cmp_eq_u32_e64 s[6:7], 0, v3
	s_nop 1
	v_mbcnt_lo_u32_b32 v4, s0, 0
	v_mbcnt_lo_u32_b32 v5, s6, 0
	v_mbcnt_hi_u32_b32 v4, s1, v4
	v_mbcnt_hi_u32_b32 v5, s7, v5
	s_bcnt1_i32_b64 s14, s[0:1]
	s_bcnt1_i32_b64 s15, s[6:7]
	v_add_u32_e32 v4, s2, v4
	s_add_i32 s14, s2, s14
	s_nop 0
	v_add_u32_e32 v5, s14, v5
	s_add_i32 s2, s14, s15
	v_cndmask_b32_e64 v6, v6, v4, s[0:1]
	v_cndmask_b32_e64 v7, v7, v5, s[6:7]
	v_cmp_eq_u32_e64 s[0:1], 1, v2
	v_cmp_eq_u32_e64 s[6:7], 1, v3
	s_nop 1
	v_mbcnt_lo_u32_b32 v4, s0, 0
	v_mbcnt_lo_u32_b32 v5, s6, 0
	v_mbcnt_hi_u32_b32 v4, s1, v4
	v_mbcnt_hi_u32_b32 v5, s7, v5
	s_bcnt1_i32_b64 s14, s[0:1]
	s_bcnt1_i32_b64 s15, s[6:7]
	v_add_u32_e32 v4, s2, v4
	s_add_i32 s14, s2, s14
	s_nop 0
	v_add_u32_e32 v5, s14, v5
	s_add_i32 s2, s14, s15
	v_cndmask_b32_e64 v6, v6, v4, s[0:1]
	v_cndmask_b32_e64 v7, v7, v5, s[6:7]
	v_cmp_eq_u32_e64 s[0:1], 2, v2
	v_cmp_eq_u32_e64 s[6:7], 2, v3
	s_nop 1
	v_mbcnt_lo_u32_b32 v4, s0, 0
	v_mbcnt_lo_u32_b32 v5, s6, 0
	v_mbcnt_hi_u32_b32 v4, s1, v4
	v_mbcnt_hi_u32_b32 v5, s7, v5
	s_bcnt1_i32_b64 s14, s[0:1]
	s_bcnt1_i32_b64 s15, s[6:7]
	v_add_u32_e32 v4, s2, v4
	s_add_i32 s14, s2, s14
	s_nop 0
	v_add_u32_e32 v5, s14, v5
	s_add_i32 s2, s14, s15
	v_cndmask_b32_e64 v6, v6, v4, s[0:1]
	v_cndmask_b32_e64 v7, v7, v5, s[6:7]
	v_cmp_eq_u32_e64 s[0:1], 3, v2
	v_cmp_eq_u32_e64 s[6:7], 3, v3
	s_nop 1
	v_mbcnt_lo_u32_b32 v4, s0, 0
	v_mbcnt_lo_u32_b32 v5, s6, 0
	v_mbcnt_hi_u32_b32 v4, s1, v4
	v_mbcnt_hi_u32_b32 v5, s7, v5
	s_bcnt1_i32_b64 s14, s[0:1]
	s_bcnt1_i32_b64 s15, s[6:7]
	v_add_u32_e32 v4, s2, v4
	s_add_i32 s14, s2, s14
	s_nop 0
	v_add_u32_e32 v5, s14, v5
	s_add_i32 s2, s14, s15
	v_cndmask_b32_e64 v6, v6, v4, s[0:1]
	v_cndmask_b32_e64 v7, v7, v5, s[6:7]
	v_cmp_eq_u32_e64 s[0:1], 4, v2
	v_cmp_eq_u32_e64 s[6:7], 4, v3
	s_nop 1
	v_mbcnt_lo_u32_b32 v4, s0, 0
	v_mbcnt_lo_u32_b32 v5, s6, 0
	v_mbcnt_hi_u32_b32 v4, s1, v4
	v_mbcnt_hi_u32_b32 v5, s7, v5
	s_bcnt1_i32_b64 s14, s[0:1]
	s_bcnt1_i32_b64 s15, s[6:7]
	v_add_u32_e32 v4, s2, v4
	s_add_i32 s14, s2, s14
	s_nop 0
	v_add_u32_e32 v5, s14, v5
	s_add_i32 s2, s14, s15
	v_cndmask_b32_e64 v6, v6, v4, s[0:1]
	v_cndmask_b32_e64 v7, v7, v5, s[6:7]
	v_cmp_eq_u32_e64 s[0:1], 5, v2
	v_cmp_eq_u32_e64 s[6:7], 5, v3
	s_nop 1
	v_mbcnt_lo_u32_b32 v4, s0, 0
	v_mbcnt_lo_u32_b32 v5, s6, 0
	v_mbcnt_hi_u32_b32 v4, s1, v4
	v_mbcnt_hi_u32_b32 v5, s7, v5
	s_bcnt1_i32_b64 s14, s[0:1]
	s_bcnt1_i32_b64 s15, s[6:7]
	v_add_u32_e32 v4, s2, v4
	s_add_i32 s14, s2, s14
	s_nop 0
	v_add_u32_e32 v5, s14, v5
	s_add_i32 s2, s14, s15
	v_cndmask_b32_e64 v6, v6, v4, s[0:1]
	v_cndmask_b32_e64 v7, v7, v5, s[6:7]
	v_cmp_eq_u32_e64 s[0:1], 6, v2
	v_cmp_eq_u32_e64 s[6:7], 6, v3
	s_nop 1
	v_mbcnt_lo_u32_b32 v4, s0, 0
	v_mbcnt_lo_u32_b32 v5, s6, 0
	v_mbcnt_hi_u32_b32 v4, s1, v4
	v_mbcnt_hi_u32_b32 v5, s7, v5
	s_bcnt1_i32_b64 s14, s[0:1]
	s_bcnt1_i32_b64 s15, s[6:7]
	v_add_u32_e32 v4, s2, v4
	s_add_i32 s14, s2, s14
	s_nop 0
	v_add_u32_e32 v5, s14, v5
	s_add_i32 s2, s14, s15
	v_cndmask_b32_e64 v6, v6, v4, s[0:1]
	v_cndmask_b32_e64 v7, v7, v5, s[6:7]
	v_cmp_eq_u32_e64 s[0:1], 7, v2
	v_cmp_eq_u32_e64 s[6:7], 7, v3
	s_nop 1
	v_mbcnt_lo_u32_b32 v4, s0, 0
	v_mbcnt_lo_u32_b32 v5, s6, 0
	v_mbcnt_hi_u32_b32 v4, s1, v4
	v_mbcnt_hi_u32_b32 v5, s7, v5
	s_bcnt1_i32_b64 s14, s[0:1]
	s_bcnt1_i32_b64 s15, s[6:7]
	v_add_u32_e32 v4, s2, v4
	s_add_i32 s14, s2, s14
	s_nop 0
	v_add_u32_e32 v5, s14, v5
	s_add_i32 s2, s14, s15
	v_cndmask_b32_e64 v6, v6, v4, s[0:1]
	v_cndmask_b32_e64 v7, v7, v5, s[6:7]
	v_lshrrev_b32_e32 v8, 6, v131
	v_mul_u32_u24_e32 v8, 0x2400, v8
	v_lshl_add_u32 v9, v6, 2, v8
	v_lshl_add_u32 v10, v7, 2, v8
	ds_write_b32 v9, v156 offset:1536
	ds_write_b32 v10, v157 offset:1536
	ds_write_b32 v9, v73 offset:2048
	ds_write_b32 v10, v158 offset:2048
	s_waitcnt vmcnt(0) lgkmcnt(0)
; __device__ __forceinline__ unsigned cvt_pk_bf16(float lo, float hi) { unsigned r; asm volatile("v_cvt_pk_bf16_f32 %0, %1, %2" : "=v"(r) : "v"(lo), "v"(hi)); return r; }
; __device__ __forceinline__ float bflo(unsigned w) { return __uint_as_float(w << 16); }
; __device__ __forceinline__ float bfhi(unsigned w) { return __uint_as_float(w & 0xffff0000u); }
; __device__ void ph_peer(const float* __restrict__ SC, const bf16_t* __restrict__ H  , const float* __restrict__ gffn, const unsigned char* __restrict__ U, const unsigned char* __restrict__ V, float* X, const float* __restrict__ fgain) {
;     ...
;         {   const u32x4* hp = (const u32x4*)(H + (size_t)tok * 1024 + 64 * sub);
; #pragma unroll
;             for (int q = 0; q < 8; ++q) { const u32x4 w = hp[q];
;                 const float4 ga = *(const float4*)(gffn + 64 * sub + q * 8), gb = *(const float4*)(gffn + 64 * sub + q * 8 + 4);
;                 hf2[q * 4 + 0] = cvt_pk_bf16(bflo(w.x) * rstd * ga.x, bfhi(w.x) * rstd * ga.y);
;                 hf2[q * 4 + 1] = cvt_pk_bf16(bflo(w.y) * rstd * ga.z, bfhi(w.y) * rstd * ga.w);
;                 hf2[q * 4 + 2] = cvt_pk_bf16(bflo(w.z) * rstd * gb.x, bfhi(w.z) * rstd * gb.y);
;                 hf2[q * 4 + 3] = cvt_pk_bf16(bflo(w.w) * rstd * gb.z, bfhi(w.w) * rstd * gb.w); } }
	v_lshlrev_b32_e32 v2, 16, v218
	v_and_b32_e32 v3, 0xffff0000, v218
	v_lshlrev_b32_e32 v4, 16, v219
	v_and_b32_e32 v5, 0xffff0000, v219
	v_pk_mul_f32 v[2:3], v[2:3], v[12:13] op_sel_hi:[1,0]
	v_pk_mul_f32 v[4:5], v[4:5], v[12:13] op_sel_hi:[1,0]
	v_pk_mul_f32 v[2:3], v[2:3], v[64:65]
	v_pk_mul_f32 v[4:5], v[4:5], v[66:67]
	v_cvt_pk_bf16_f32 v212, v2, v3
	v_cvt_pk_bf16_f32 v213, v4, v5
	v_lshlrev_b32_e32 v2, 16, v220
	v_and_b32_e32 v3, 0xffff0000, v220
	v_lshlrev_b32_e32 v4, 16, v221
	v_and_b32_e32 v5, 0xffff0000, v221
	v_pk_mul_f32 v[2:3], v[2:3], v[12:13] op_sel_hi:[1,0]
	v_pk_mul_f32 v[4:5], v[4:5], v[12:13] op_sel_hi:[1,0]
	v_pk_mul_f32 v[2:3], v[2:3], v[68:69]
	v_pk_mul_f32 v[4:5], v[4:5], v[70:71]
	v_cvt_pk_bf16_f32 v214, v2, v3
	v_cvt_pk_bf16_f32 v215, v4, v5
	v_lshlrev_b32_e32 v2, 16, v222
	v_and_b32_e32 v3, 0xffff0000, v222
	v_lshlrev_b32_e32 v4, 16, v223
	v_and_b32_e32 v5, 0xffff0000, v223
	v_pk_mul_f32 v[2:3], v[2:3], v[12:13] op_sel_hi:[1,0]
	v_pk_mul_f32 v[4:5], v[4:5], v[12:13] op_sel_hi:[1,0]
	v_pk_mul_f32 v[2:3], v[2:3], v[32:33]
	v_pk_mul_f32 v[4:5], v[4:5], v[34:35]
	v_cvt_pk_bf16_f32 v218, v2, v3
	v_cvt_pk_bf16_f32 v219, v4, v5
	v_lshlrev_b32_e32 v2, 16, v224
	v_and_b32_e32 v3, 0xffff0000, v224
	v_lshlrev_b32_e32 v4, 16, v225
	v_and_b32_e32 v5, 0xffff0000, v225
	v_pk_mul_f32 v[2:3], v[2:3], v[12:13] op_sel_hi:[1,0]
	v_pk_mul_f32 v[4:5], v[4:5], v[12:13] op_sel_hi:[1,0]
	v_pk_mul_f32 v[2:3], v[2:3], v[36:37]
	v_pk_mul_f32 v[4:5], v[4:5], v[38:39]
	v_cvt_pk_bf16_f32 v220, v2, v3
	v_cvt_pk_bf16_f32 v221, v4, v5
	v_lshlrev_b32_e32 v2, 16, v226
	v_and_b32_e32 v3, 0xffff0000, v226
	v_lshlrev_b32_e32 v4, 16, v227
	v_and_b32_e32 v5, 0xffff0000, v227
	v_pk_mul_f32 v[2:3], v[2:3], v[12:13] op_sel_hi:[1,0]
	v_pk_mul_f32 v[4:5], v[4:5], v[12:13] op_sel_hi:[1,0]
	v_pk_mul_f32 v[2:3], v[2:3], v[40:41]
	v_pk_mul_f32 v[4:5], v[4:5], v[42:43]
	v_cvt_pk_bf16_f32 v222, v2, v3
	v_cvt_pk_bf16_f32 v223, v4, v5
	v_lshlrev_b32_e32 v2, 16, v228
	v_and_b32_e32 v3, 0xffff0000, v228
	v_lshlrev_b32_e32 v4, 16, v229
	v_and_b32_e32 v5, 0xffff0000, v229
	v_pk_mul_f32 v[2:3], v[2:3], v[12:13] op_sel_hi:[1,0]
	v_pk_mul_f32 v[4:5], v[4:5], v[12:13] op_sel_hi:[1,0]
	v_pk_mul_f32 v[2:3], v[2:3], v[44:45]
	v_pk_mul_f32 v[4:5], v[4:5], v[46:47]
	v_cvt_pk_bf16_f32 v224, v2, v3
	v_cvt_pk_bf16_f32 v225, v4, v5
	v_lshlrev_b32_e32 v2, 16, v230
	v_and_b32_e32 v3, 0xffff0000, v230
	v_lshlrev_b32_e32 v4, 16, v231
	v_and_b32_e32 v5, 0xffff0000, v231
	v_pk_mul_f32 v[2:3], v[2:3], v[12:13] op_sel_hi:[1,0]
	v_pk_mul_f32 v[4:5], v[4:5], v[12:13] op_sel_hi:[1,0]
	v_pk_mul_f32 v[2:3], v[2:3], v[48:49]
	v_pk_mul_f32 v[4:5], v[4:5], v[50:51]
	v_cvt_pk_bf16_f32 v226, v2, v3
	v_cvt_pk_bf16_f32 v227, v4, v5
	v_lshlrev_b32_e32 v2, 16, v232
	v_and_b32_e32 v3, 0xffff0000, v232
	v_lshlrev_b32_e32 v4, 16, v233
	v_and_b32_e32 v5, 0xffff0000, v233
	v_pk_mul_f32 v[2:3], v[2:3], v[12:13] op_sel_hi:[1,0]
	v_pk_mul_f32 v[4:5], v[4:5], v[12:13] op_sel_hi:[1,0]
	v_pk_mul_f32 v[2:3], v[2:3], v[52:53]
	v_pk_mul_f32 v[4:5], v[4:5], v[54:55]
	v_cvt_pk_bf16_f32 v228, v2, v3
	v_cvt_pk_bf16_f32 v229, v4, v5
	v_lshlrev_b32_e32 v2, 16, v234
	v_and_b32_e32 v3, 0xffff0000, v234
	v_lshlrev_b32_e32 v4, 16, v235
	v_and_b32_e32 v5, 0xffff0000, v235
	v_pk_mul_f32 v[2:3], v[2:3], v[12:13] op_sel_hi:[1,0]
	v_pk_mul_f32 v[4:5], v[4:5], v[12:13] op_sel_hi:[1,0]
	v_pk_mul_f32 v[2:3], v[2:3], v[56:57]
	v_pk_mul_f32 v[4:5], v[4:5], v[58:59]
	v_cvt_pk_bf16_f32 v230, v2, v3
	v_cvt_pk_bf16_f32 v231, v4, v5
	v_lshlrev_b32_e32 v2, 16, v236
	v_and_b32_e32 v3, 0xffff0000, v236
	v_lshlrev_b32_e32 v4, 16, v237
	v_and_b32_e32 v5, 0xffff0000, v237
	v_pk_mul_f32 v[2:3], v[2:3], v[12:13] op_sel_hi:[1,0]
	v_pk_mul_f32 v[4:5], v[4:5], v[12:13] op_sel_hi:[1,0]
	v_pk_mul_f32 v[2:3], v[2:3], v[60:61]
	v_pk_mul_f32 v[4:5], v[4:5], v[62:63]
	v_cvt_pk_bf16_f32 v232, v2, v3
	v_cvt_pk_bf16_f32 v233, v4, v5
	v_lshlrev_b32_e32 v2, 16, v238
	v_and_b32_e32 v3, 0xffff0000, v238
	v_lshlrev_b32_e32 v4, 16, v239
	v_and_b32_e32 v5, 0xffff0000, v239
	v_pk_mul_f32 v[2:3], v[2:3], v[12:13] op_sel_hi:[1,0]
	v_pk_mul_f32 v[4:5], v[4:5], v[12:13] op_sel_hi:[1,0]
	v_pk_mul_f32 v[2:3], v[2:3], v[98:99]
	v_pk_mul_f32 v[4:5], v[4:5], v[100:101]
	v_cvt_pk_bf16_f32 v234, v2, v3
	v_cvt_pk_bf16_f32 v235, v4, v5
	v_lshlrev_b32_e32 v2, 16, v240
	v_and_b32_e32 v3, 0xffff0000, v240
	v_lshlrev_b32_e32 v4, 16, v241
	v_and_b32_e32 v5, 0xffff0000, v241
	v_pk_mul_f32 v[2:3], v[2:3], v[12:13] op_sel_hi:[1,0]
	v_pk_mul_f32 v[4:5], v[4:5], v[12:13] op_sel_hi:[1,0]
	v_pk_mul_f32 v[2:3], v[2:3], v[102:103]
	v_pk_mul_f32 v[4:5], v[4:5], v[104:105]
	v_cvt_pk_bf16_f32 v236, v2, v3
	v_cvt_pk_bf16_f32 v237, v4, v5
	v_lshlrev_b32_e32 v2, 16, v242
	v_and_b32_e32 v3, 0xffff0000, v242
	v_lshlrev_b32_e32 v4, 16, v243
	v_and_b32_e32 v5, 0xffff0000, v243
	v_pk_mul_f32 v[2:3], v[2:3], v[12:13] op_sel_hi:[1,0]
	v_pk_mul_f32 v[4:5], v[4:5], v[12:13] op_sel_hi:[1,0]
	v_pk_mul_f32 v[2:3], v[2:3], v[106:107]
	v_pk_mul_f32 v[4:5], v[4:5], v[108:109]
	v_cvt_pk_bf16_f32 v238, v2, v3
	v_cvt_pk_bf16_f32 v239, v4, v5
	v_lshlrev_b32_e32 v2, 16, v244
	v_and_b32_e32 v3, 0xffff0000, v244
	v_lshlrev_b32_e32 v4, 16, v245
	v_and_b32_e32 v5, 0xffff0000, v245
	v_pk_mul_f32 v[2:3], v[2:3], v[12:13] op_sel_hi:[1,0]
	v_pk_mul_f32 v[4:5], v[4:5], v[12:13] op_sel_hi:[1,0]
	v_pk_mul_f32 v[2:3], v[2:3], v[110:111]
	v_pk_mul_f32 v[4:5], v[4:5], v[112:113]
	v_cvt_pk_bf16_f32 v240, v2, v3
	v_cvt_pk_bf16_f32 v241, v4, v5
	v_lshlrev_b32_e32 v2, 16, v246
	v_and_b32_e32 v3, 0xffff0000, v246
	v_lshlrev_b32_e32 v4, 16, v247
	v_and_b32_e32 v5, 0xffff0000, v247
	v_pk_mul_f32 v[2:3], v[2:3], v[12:13] op_sel_hi:[1,0]
; __device__ void ph_peer(const float* __restrict__ SC, const bf16_t* __restrict__ H  , const float* __restrict__ gffn, const unsigned char* __restrict__ U, const unsigned char* __restrict__ V, float* X, const float* __restrict__ fgain) {
;     ...
;         float acc[32];
; #pragma unroll
;         for (int i = 0; i < 32; ++i) acc[i] = 0.f;
;         __builtin_amdgcn_s_setprio(1);
; #pragma unroll 1
;         for (int it = 0; it < 32; ++it) {
;             const int src = (it * 4 + grp) & 63;
;             const int e = __shfl(it < 16 ? idx_lo : idx_hi, src);
;             const float gt = __shfl(it < 16 ? g_lo : g_hi, src);
;             const u32x4* up = (const u32x4*)(U + (size_t)e * 768 + 48 * sub);
;             const u32x4 u0 = up[0], u1 = up[1], u2 = up[2];
;             u32x2 vw[2][3];
; #pragma unroll
;             for (int r = 0; r < 2; ++r) { const int ea = __builtin_amdgcn_readlane(e, 32 * r), eb = __builtin_amdgcn_readlane(e, 32 * r + 16);
;                 const u32x2* vp = (const u32x2*)(V + (size_t)(half ? eb : ea) * 768 + 24 * c32); vw[r][0] = vp[0]; vw[r][1] = vp[1]; vw[r][2] = vp[2]; }
;             float d0 = 0.f, d1 = 0.f, d2 = 0.f, d3 = 0.f;
;             {   const v6u_t p0 = (v6u_t){u0.x, u0.y, u0.z, u0.w, u1.x, u1.y};
;                 const v32bf_t r0 = __builtin_amdgcn_cvt_scalef32_pk32_bf16_fp6(p0, 1.0f);
; #pragma unroll
;                 for (int k = 0; k < 16; k += 4) { d0 = dot2pb(r0[2 * k], r0[2 * k + 1], hf2[k], d0); d1 = dot2pb(r0[2 * k + 2], r0[2 * k + 3], hf2[k + 1], d1);
;                     d2 = dot2pb(r0[2 * k + 4], r0[2 * k + 5], hf2[k + 2], d2); d3 = dot2pb(r0[2 * k + 6], r0[2 * k + 7], hf2[k + 3], d3); } }
;             {   const v6u_t p1 = (v6u_t){u1.z, u1.w, u2.x, u2.y, u2.z, u2.w};
;                 const v32bf_t r1 = __builtin_amdgcn_cvt_scalef32_pk32_bf16_fp6(p1, 1.0f);
; #pragma unroll
;                 for (int k = 0; k < 16; k += 4) { d0 = dot2pb(r1[2 * k], r1[2 * k + 1], hf2[16 + k], d0); d1 = dot2pb(r1[2 * k + 2], r1[2 * k + 3], hf2[16 + k + 1], d1);
;                     d2 = dot2pb(r1[2 * k + 4], r1[2 * k + 5], hf2[16 + k + 2], d2); d3 = dot2pb(r1[2 * k + 6], r1[2 * k + 7], hf2[16 + k + 3], d3); } }
;             const float d = row16_sum((d0 + d1) + (d2 + d3)) * FP6_INV;
	v_pk_mul_f32 v[4:5], v[4:5], v[12:13] op_sel_hi:[1,0]
	v_pk_mul_f32 v[2:3], v[2:3], v[114:115]
	v_pk_mul_f32 v[4:5], v[4:5], v[116:117]
	v_cvt_pk_bf16_f32 v242, v2, v3
	v_cvt_pk_bf16_f32 v243, v4, v5
	v_lshlrev_b32_e32 v2, 16, v248
	v_and_b32_e32 v3, 0xffff0000, v248
	v_lshlrev_b32_e32 v4, 16, v249
	v_and_b32_e32 v5, 0xffff0000, v249
	v_pk_mul_f32 v[2:3], v[2:3], v[12:13] op_sel_hi:[1,0]
	v_pk_mul_f32 v[4:5], v[4:5], v[12:13] op_sel_hi:[1,0]
	v_pk_mul_f32 v[2:3], v[2:3], v[118:119]
	v_pk_mul_f32 v[4:5], v[4:5], v[120:121]
	v_cvt_pk_bf16_f32 v244, v2, v3
	v_cvt_pk_bf16_f32 v245, v4, v5
	s_setprio 1
	v_mov_b32_e32 v126, 0
	s_mov_b32 s0, 0
	s_mov_b32 s1, 0
	v_mov_b32_e32 v127, v126
	v_mov_b32_e32 v144, v126
	v_mov_b32_e32 v145, v126
	v_mov_b32_e32 v122, v126
	v_mov_b32_e32 v123, v126
	v_mov_b32_e32 v124, v126
	v_mov_b32_e32 v125, v126
	v_mov_b32_e32 v114, v126
	v_mov_b32_e32 v115, v126
	v_mov_b32_e32 v118, v126
	v_mov_b32_e32 v119, v126
	v_mov_b32_e32 v116, v126
	v_mov_b32_e32 v117, v126
	v_mov_b32_e32 v120, v126
	v_mov_b32_e32 v121, v126
	v_mov_b32_e32 v106, v126
	v_mov_b32_e32 v107, v126
	v_mov_b32_e32 v110, v126
	v_mov_b32_e32 v111, v126
	v_mov_b32_e32 v108, v126
	v_mov_b32_e32 v109, v126
	v_mov_b32_e32 v112, v126
	v_mov_b32_e32 v113, v126
	v_mov_b32_e32 v98, v126
	v_mov_b32_e32 v99, v126
	v_mov_b32_e32 v102, v126
	v_mov_b32_e32 v103, v126
	v_mov_b32_e32 v100, v126
	v_mov_b32_e32 v101, v126
	v_mov_b32_e32 v104, v126
	v_mov_b32_e32 v105, v126
	s_movk_i32 s14, 0x300
	s_mov_b32 s16, 0x3e6d3388
	s_mov_b32 s24, 0x3f07dc22
	s_mov_b32 s28, 0x3f35f0e3
	s_mov_b32 s30, 0xbe11a98e
	s_mov_b32 s36, 0x3e027906
	s_barrier
	v_lshrrev_b32_e32 v61, 6, v131
	v_mul_u32_u24_e32 v61, 0x2400, v61
	v_lshl_add_u32 v61, v91, 2, v61
	s_mov_b32 s1, 0
	ds_read_b32 v56, v61
	v_add_u32_e32 v61, 16, v61
	s_add_i32 s1, s1, 1
	s_waitcnt lgkmcnt(0)
	v_mad_u32_u24 v0, v56, s14, v92
	global_load_dwordx4 v[32:35], v0, s[46:47]
	global_load_dwordx4 v[36:39], v0, s[46:47] offset:16
	global_load_dwordx4 v[40:43], v0, s[46:47] offset:32
.Lpeer_uloop:
	ds_read_b32 v58, v61 offset:1520
	s_waitcnt lgkmcnt(0)
	v_mad_u32_u24 v0, v58, s14, v92
	global_load_dwordx4 v[44:47], v0, s[46:47]
	global_load_dwordx4 v[48:51], v0, s[46:47] offset:16
	global_load_dwordx4 v[52:55], v0, s[46:47] offset:32
	s_waitcnt vmcnt(3)
	v_cvt_scalef32_pk32_bf16_fp6 v[0:15], v[32:37], 1.0
	v_dot2_f32_bf16 v23, v0, v95, 0
	v_dot2_f32_bf16 v25, v1, v159, 0
	v_dot2_f32_bf16 v22, v2, v160, 0
	v_dot2_f32_bf16 v24, v3, v161, 0
	v_dot2c_f32_bf16_e32 v23, v4, v180
	v_dot2c_f32_bf16_e32 v25, v5, v181
	v_dot2c_f32_bf16_e32 v22, v6, v182
	v_dot2c_f32_bf16_e32 v24, v7, v183
	v_dot2c_f32_bf16_e32 v23, v8, v184
	v_dot2c_f32_bf16_e32 v25, v9, v185
	v_dot2c_f32_bf16_e32 v22, v10, v186
	v_dot2c_f32_bf16_e32 v24, v11, v187
	v_dot2c_f32_bf16_e32 v23, v12, v188
	v_dot2c_f32_bf16_e32 v25, v13, v189
	v_dot2c_f32_bf16_e32 v22, v14, v190
	v_dot2c_f32_bf16_e32 v24, v15, v191
	v_cvt_scalef32_pk32_bf16_fp6 v[0:15], v[38:43], 1.0
	v_dot2c_f32_bf16_e32 v23, v0, v192
	v_dot2c_f32_bf16_e32 v25, v1, v193
	v_dot2c_f32_bf16_e32 v22, v2, v194
	v_dot2c_f32_bf16_e32 v24, v3, v195
	v_dot2c_f32_bf16_e32 v23, v4, v196
	v_dot2c_f32_bf16_e32 v25, v5, v197
	v_dot2c_f32_bf16_e32 v22, v6, v198
	v_dot2c_f32_bf16_e32 v24, v7, v199
	v_dot2c_f32_bf16_e32 v23, v8, v200
	v_dot2c_f32_bf16_e32 v25, v9, v201
	v_dot2c_f32_bf16_e32 v22, v10, v202
	v_dot2c_f32_bf16_e32 v24, v11, v203
	v_dot2c_f32_bf16_e32 v23, v12, v204
	v_dot2c_f32_bf16_e32 v25, v13, v205
	v_dot2c_f32_bf16_e32 v22, v14, v206
	v_dot2c_f32_bf16_e32 v24, v15, v207
	s_nop 2
	v_pk_add_f32 v[0:1], v[24:25], v[22:23]
	s_nop 0
	v_add_f32_e32 v246, v0, v1
	ds_read_b32 v56, v61
	v_add_u32_e32 v61, 16, v61
	s_add_i32 s1, s1, 1
	s_waitcnt lgkmcnt(0)
	v_mad_u32_u24 v0, v56, s14, v92
	global_load_dwordx4 v[32:35], v0, s[46:47]
	global_load_dwordx4 v[36:39], v0, s[46:47] offset:16
	global_load_dwordx4 v[40:43], v0, s[46:47] offset:32
	s_waitcnt vmcnt(3)
	v_cvt_scalef32_pk32_bf16_fp6 v[0:15], v[44:49], 1.0
	v_dot2_f32_bf16 v23, v0, v212, 0
	v_dot2_f32_bf16 v25, v1, v213, 0
	v_dot2_f32_bf16 v22, v2, v214, 0
	v_dot2_f32_bf16 v24, v3, v215, 0
	v_dot2c_f32_bf16_e32 v23, v4, v218
	v_dot2c_f32_bf16_e32 v25, v5, v219
	v_dot2c_f32_bf16_e32 v22, v6, v220
	v_dot2c_f32_bf16_e32 v24, v7, v221
	v_dot2c_f32_bf16_e32 v23, v8, v222
	v_dot2c_f32_bf16_e32 v25, v9, v223
	v_dot2c_f32_bf16_e32 v22, v10, v224
	v_dot2c_f32_bf16_e32 v24, v11, v225
	v_dot2c_f32_bf16_e32 v23, v12, v226
	v_dot2c_f32_bf16_e32 v25, v13, v227
	v_dot2c_f32_bf16_e32 v22, v14, v228
	v_dot2c_f32_bf16_e32 v24, v15, v229
	v_cvt_scalef32_pk32_bf16_fp6 v[0:15], v[50:55], 1.0
	v_dot2c_f32_bf16_e32 v23, v0, v230
	v_dot2c_f32_bf16_e32 v25, v1, v231
	v_dot2c_f32_bf16_e32 v22, v2, v232
	v_dot2c_f32_bf16_e32 v24, v3, v233
	v_dot2c_f32_bf16_e32 v23, v4, v234
	v_dot2c_f32_bf16_e32 v25, v5, v235
	v_dot2c_f32_bf16_e32 v22, v6, v236
	v_dot2c_f32_bf16_e32 v24, v7, v237
	v_dot2c_f32_bf16_e32 v23, v8, v238
	v_dot2c_f32_bf16_e32 v25, v9, v239
	v_dot2c_f32_bf16_e32 v22, v10, v240
	v_dot2c_f32_bf16_e32 v24, v11, v241
	v_dot2c_f32_bf16_e32 v23, v12, v242
	v_dot2c_f32_bf16_e32 v25, v13, v243
	v_dot2c_f32_bf16_e32 v22, v14, v244
	v_dot2c_f32_bf16_e32 v24, v15, v245
	s_nop 2
	v_pk_add_f32 v[0:1], v[24:25], v[22:23]
	s_nop 0
	v_add_f32_e32 v250, v0, v1
	ds_read_b32 v58, v61 offset:1520
	s_waitcnt lgkmcnt(0)
	v_mad_u32_u24 v0, v58, s14, v92
	global_load_dwordx4 v[44:47], v0, s[46:47]
	global_load_dwordx4 v[48:51], v0, s[46:47] offset:16
	global_load_dwordx4 v[52:55], v0, s[46:47] offset:32
	s_waitcnt vmcnt(3)
; __device__ __forceinline__ float gelu1(float v) { const f32x2 r = gelu_pk((f32x2){v, v}); return r.x; }
; __device__ void ph_peer(const float* __restrict__ SC, const bf16_t* __restrict__ H  , const float* __restrict__ gffn, const unsigned char* __restrict__ U, const unsigned char* __restrict__ V, float* X, const float* __restrict__ fgain) {
;     ...
;         for (int it = 0; it < 32; ++it) {
;             const int src = (it * 4 + grp) & 63;
;             const int e = __shfl(it < 16 ? idx_lo : idx_hi, src);
;             const float gt = __shfl(it < 16 ? g_lo : g_hi, src);
;             const u32x4* up = (const u32x4*)(U + (size_t)e * 768 + 48 * sub);
;             const u32x4 u0 = up[0], u1 = up[1], u2 = up[2];
;             u32x2 vw[2][3];
; #pragma unroll
;             for (int r = 0; r < 2; ++r) { const int ea = __builtin_amdgcn_readlane(e, 32 * r), eb = __builtin_amdgcn_readlane(e, 32 * r + 16);
;                 const u32x2* vp = (const u32x2*)(V + (size_t)(half ? eb : ea) * 768 + 24 * c32); vw[r][0] = vp[0]; vw[r][1] = vp[1]; vw[r][2] = vp[2]; }
;             float d0 = 0.f, d1 = 0.f, d2 = 0.f, d3 = 0.f;
;             {   const v6u_t p0 = (v6u_t){u0.x, u0.y, u0.z, u0.w, u1.x, u1.y};
;                 const v32bf_t r0 = __builtin_amdgcn_cvt_scalef32_pk32_bf16_fp6(p0, 1.0f);
; #pragma unroll
;                 for (int k = 0; k < 16; k += 4) { d0 = dot2pb(r0[2 * k], r0[2 * k + 1], hf2[k], d0); d1 = dot2pb(r0[2 * k + 2], r0[2 * k + 3], hf2[k + 1], d1);
;                     d2 = dot2pb(r0[2 * k + 4], r0[2 * k + 5], hf2[k + 2], d2); d3 = dot2pb(r0[2 * k + 6], r0[2 * k + 7], hf2[k + 3], d3); } }
;             {   const v6u_t p1 = (v6u_t){u1.z, u1.w, u2.x, u2.y, u2.z, u2.w};
;                 const v32bf_t r1 = __builtin_amdgcn_cvt_scalef32_pk32_bf16_fp6(p1, 1.0f);
; #pragma unroll
;                 for (int k = 0; k < 16; k += 4) { d0 = dot2pb(r1[2 * k], r1[2 * k + 1], hf2[16 + k], d0); d1 = dot2pb(r1[2 * k + 2], r1[2 * k + 3], hf2[16 + k + 1], d1);
;                     d2 = dot2pb(r1[2 * k + 4], r1[2 * k + 5], hf2[16 + k + 2], d2); d3 = dot2pb(r1[2 * k + 6], r1[2 * k + 7], hf2[16 + k + 3], d3); } }
;             const float d = row16_sum((d0 + d1) + (d2 + d3)) * FP6_INV;
;             const float a = gt * gelu1(d) * FP6_INV;
	v_cvt_scalef32_pk32_bf16_fp6 v[0:15], v[32:37], 1.0
	v_dot2_f32_bf16 v23, v0, v95, 0
	v_dot2_f32_bf16 v25, v1, v159, 0
	v_dot2_f32_bf16 v22, v2, v160, 0
	v_dot2_f32_bf16 v24, v3, v161, 0
	v_dot2c_f32_bf16_e32 v23, v4, v180
	v_dot2c_f32_bf16_e32 v25, v5, v181
	v_dot2c_f32_bf16_e32 v22, v6, v182
	v_dot2c_f32_bf16_e32 v24, v7, v183
	v_dot2c_f32_bf16_e32 v23, v8, v184
	v_dot2c_f32_bf16_e32 v25, v9, v185
	v_dot2c_f32_bf16_e32 v22, v10, v186
	v_dot2c_f32_bf16_e32 v24, v11, v187
	v_dot2c_f32_bf16_e32 v23, v12, v188
	v_dot2c_f32_bf16_e32 v25, v13, v189
	v_dot2c_f32_bf16_e32 v22, v14, v190
	v_dot2c_f32_bf16_e32 v24, v15, v191
	v_cvt_scalef32_pk32_bf16_fp6 v[0:15], v[38:43], 1.0
	v_dot2c_f32_bf16_e32 v23, v0, v192
	v_dot2c_f32_bf16_e32 v25, v1, v193
	v_dot2c_f32_bf16_e32 v22, v2, v194
	v_dot2c_f32_bf16_e32 v24, v3, v195
	v_dot2c_f32_bf16_e32 v23, v4, v196
	v_dot2c_f32_bf16_e32 v25, v5, v197
	v_dot2c_f32_bf16_e32 v22, v6, v198
	v_dot2c_f32_bf16_e32 v24, v7, v199
	v_dot2c_f32_bf16_e32 v23, v8, v200
	v_dot2c_f32_bf16_e32 v25, v9, v201
	v_dot2c_f32_bf16_e32 v22, v10, v202
	v_dot2c_f32_bf16_e32 v24, v11, v203
	v_dot2c_f32_bf16_e32 v23, v12, v204
	v_dot2c_f32_bf16_e32 v25, v13, v205
	v_dot2c_f32_bf16_e32 v22, v14, v206
	v_dot2c_f32_bf16_e32 v24, v15, v207
	s_nop 2
	v_pk_add_f32 v[0:1], v[24:25], v[22:23]
	s_nop 0
	v_add_f32_e32 v247, v0, v1
	ds_read_b32 v56, v61
	v_add_u32_e32 v61, 16, v61
	s_add_i32 s1, s1, 1
	s_waitcnt lgkmcnt(0)
	v_mad_u32_u24 v0, v56, s14, v92
	global_load_dwordx4 v[32:35], v0, s[46:47]
	global_load_dwordx4 v[36:39], v0, s[46:47] offset:16
	global_load_dwordx4 v[40:43], v0, s[46:47] offset:32
	s_waitcnt vmcnt(3)
	v_cvt_scalef32_pk32_bf16_fp6 v[0:15], v[44:49], 1.0
	v_dot2_f32_bf16 v23, v0, v212, 0
	v_dot2_f32_bf16 v25, v1, v213, 0
	v_dot2_f32_bf16 v22, v2, v214, 0
	v_dot2_f32_bf16 v24, v3, v215, 0
	v_dot2c_f32_bf16_e32 v23, v4, v218
	v_dot2c_f32_bf16_e32 v25, v5, v219
	v_dot2c_f32_bf16_e32 v22, v6, v220
	v_dot2c_f32_bf16_e32 v24, v7, v221
	v_dot2c_f32_bf16_e32 v23, v8, v222
	v_dot2c_f32_bf16_e32 v25, v9, v223
	v_dot2c_f32_bf16_e32 v22, v10, v224
	v_dot2c_f32_bf16_e32 v24, v11, v225
	v_dot2c_f32_bf16_e32 v23, v12, v226
	v_dot2c_f32_bf16_e32 v25, v13, v227
	v_dot2c_f32_bf16_e32 v22, v14, v228
	v_dot2c_f32_bf16_e32 v24, v15, v229
	v_cvt_scalef32_pk32_bf16_fp6 v[0:15], v[50:55], 1.0
	v_dot2c_f32_bf16_e32 v23, v0, v230
	v_dot2c_f32_bf16_e32 v25, v1, v231
	v_dot2c_f32_bf16_e32 v22, v2, v232
	v_dot2c_f32_bf16_e32 v24, v3, v233
	v_dot2c_f32_bf16_e32 v23, v4, v234
	v_dot2c_f32_bf16_e32 v25, v5, v235
	v_dot2c_f32_bf16_e32 v22, v6, v236
	v_dot2c_f32_bf16_e32 v24, v7, v237
	v_dot2c_f32_bf16_e32 v23, v8, v238
	v_dot2c_f32_bf16_e32 v25, v9, v239
	v_dot2c_f32_bf16_e32 v22, v10, v240
	v_dot2c_f32_bf16_e32 v24, v11, v241
	v_dot2c_f32_bf16_e32 v23, v12, v242
	v_dot2c_f32_bf16_e32 v25, v13, v243
	v_dot2c_f32_bf16_e32 v22, v14, v244
	v_dot2c_f32_bf16_e32 v24, v15, v245
	s_nop 2
	v_pk_add_f32 v[0:1], v[24:25], v[22:23]
	s_nop 0
	v_add_f32_e32 v216, v0, v1
	ds_read_b32 v58, v61 offset:1520
	s_waitcnt lgkmcnt(0)
	v_mad_u32_u24 v0, v58, s14, v92
	global_load_dwordx4 v[44:47], v0, s[46:47]
	global_load_dwordx4 v[48:51], v0, s[46:47] offset:16
	global_load_dwordx4 v[52:55], v0, s[46:47] offset:32
	s_waitcnt vmcnt(3)
	v_cvt_scalef32_pk32_bf16_fp6 v[0:15], v[32:37], 1.0
	v_dot2_f32_bf16 v23, v0, v95, 0
	v_dot2_f32_bf16 v25, v1, v159, 0
	v_dot2_f32_bf16 v22, v2, v160, 0
	v_dot2_f32_bf16 v24, v3, v161, 0
	v_dot2c_f32_bf16_e32 v23, v4, v180
	v_dot2c_f32_bf16_e32 v25, v5, v181
	v_dot2c_f32_bf16_e32 v22, v6, v182
	v_dot2c_f32_bf16_e32 v24, v7, v183
	v_dot2c_f32_bf16_e32 v23, v8, v184
	v_dot2c_f32_bf16_e32 v25, v9, v185
	v_dot2c_f32_bf16_e32 v22, v10, v186
	v_dot2c_f32_bf16_e32 v24, v11, v187
	v_dot2c_f32_bf16_e32 v23, v12, v188
	v_dot2c_f32_bf16_e32 v25, v13, v189
	v_dot2c_f32_bf16_e32 v22, v14, v190
	v_dot2c_f32_bf16_e32 v24, v15, v191
	v_cvt_scalef32_pk32_bf16_fp6 v[0:15], v[38:43], 1.0
	v_dot2c_f32_bf16_e32 v23, v0, v192
	v_dot2c_f32_bf16_e32 v25, v1, v193
	v_dot2c_f32_bf16_e32 v22, v2, v194
	v_dot2c_f32_bf16_e32 v24, v3, v195
	v_dot2c_f32_bf16_e32 v23, v4, v196
	v_dot2c_f32_bf16_e32 v25, v5, v197
	v_dot2c_f32_bf16_e32 v22, v6, v198
	v_dot2c_f32_bf16_e32 v24, v7, v199
	v_dot2c_f32_bf16_e32 v23, v8, v200
	v_dot2c_f32_bf16_e32 v25, v9, v201
	v_dot2c_f32_bf16_e32 v22, v10, v202
	v_dot2c_f32_bf16_e32 v24, v11, v203
	v_dot2c_f32_bf16_e32 v23, v12, v204
	v_dot2c_f32_bf16_e32 v25, v13, v205
	v_dot2c_f32_bf16_e32 v22, v14, v206
	v_dot2c_f32_bf16_e32 v24, v15, v207
	s_nop 2
	v_pk_add_f32 v[0:1], v[24:25], v[22:23]
	s_nop 0
	v_add_f32_e32 v248, v0, v1
	ds_read_b32 v56, v61
	v_add_u32_e32 v61, 16, v61
	s_add_i32 s1, s1, 1
	s_waitcnt lgkmcnt(0)
	v_mad_u32_u24 v0, v56, s14, v92
	global_load_dwordx4 v[32:35], v0, s[46:47]
	global_load_dwordx4 v[36:39], v0, s[46:47] offset:16
	global_load_dwordx4 v[40:43], v0, s[46:47] offset:32
	s_waitcnt vmcnt(3)
	v_cvt_scalef32_pk32_bf16_fp6 v[0:15], v[44:49], 1.0
	v_dot2_f32_bf16 v23, v0, v212, 0
	v_dot2_f32_bf16 v25, v1, v213, 0
	v_dot2_f32_bf16 v22, v2, v214, 0
	v_dot2_f32_bf16 v24, v3, v215, 0
	v_dot2c_f32_bf16_e32 v23, v4, v218
	v_dot2c_f32_bf16_e32 v25, v5, v219
	v_dot2c_f32_bf16_e32 v22, v6, v220
	v_dot2c_f32_bf16_e32 v24, v7, v221
	v_dot2c_f32_bf16_e32 v23, v8, v222
	v_dot2c_f32_bf16_e32 v25, v9, v223
	v_dot2c_f32_bf16_e32 v22, v10, v224
	v_dot2c_f32_bf16_e32 v24, v11, v225
	v_dot2c_f32_bf16_e32 v23, v12, v226
	v_dot2c_f32_bf16_e32 v25, v13, v227
	v_dot2c_f32_bf16_e32 v22, v14, v228
	v_dot2c_f32_bf16_e32 v24, v15, v229
	v_cvt_scalef32_pk32_bf16_fp6 v[0:15], v[50:55], 1.0
	v_dot2c_f32_bf16_e32 v23, v0, v230
	v_dot2c_f32_bf16_e32 v25, v1, v231
	v_dot2c_f32_bf16_e32 v22, v2, v232
	v_dot2c_f32_bf16_e32 v24, v3, v233
	v_dot2c_f32_bf16_e32 v23, v4, v234
	v_dot2c_f32_bf16_e32 v25, v5, v235
	v_dot2c_f32_bf16_e32 v22, v6, v236
	v_dot2c_f32_bf16_e32 v24, v7, v237
	v_dot2c_f32_bf16_e32 v23, v8, v238
	v_dot2c_f32_bf16_e32 v25, v9, v239
	v_dot2c_f32_bf16_e32 v22, v10, v240
	v_dot2c_f32_bf16_e32 v24, v11, v241
	v_dot2c_f32_bf16_e32 v23, v12, v242
	v_dot2c_f32_bf16_e32 v25, v13, v243
	v_dot2c_f32_bf16_e32 v22, v14, v244
	v_dot2c_f32_bf16_e32 v24, v15, v245
	s_nop 2
	v_pk_add_f32 v[0:1], v[24:25], v[22:23]
	s_nop 0
	v_add_f32_e32 v217, v0, v1
	ds_read_b32 v58, v61 offset:1520
	s_waitcnt lgkmcnt(0)
; __device__ __forceinline__ f32x2 gelu_pk(f32x2 v) {
;     const f32x2 av = __builtin_elementwise_abs(v), d = av * 0.2316418882f + 1.0f;
;     f32x2 t; t.x = __builtin_amdgcn_rcpf(d.x); t.y = __builtin_amdgcn_rcpf(d.y);
; __device__ void ph_peer(const float* __restrict__ SC, const bf16_t* __restrict__ H  , const float* __restrict__ gffn, const unsigned char* __restrict__ U, const unsigned char* __restrict__ V, float* X, const float* __restrict__ fgain) {
;     ...
;         for (int it = 0; it < 32; ++it) {
;             const int src = (it * 4 + grp) & 63;
;             const int e = __shfl(it < 16 ? idx_lo : idx_hi, src);
;             const float gt = __shfl(it < 16 ? g_lo : g_hi, src);
;             const u32x4* up = (const u32x4*)(U + (size_t)e * 768 + 48 * sub);
;             const u32x4 u0 = up[0], u1 = up[1], u2 = up[2];
;             u32x2 vw[2][3];
; #pragma unroll
;             for (int r = 0; r < 2; ++r) { const int ea = __builtin_amdgcn_readlane(e, 32 * r), eb = __builtin_amdgcn_readlane(e, 32 * r + 16);
;                 const u32x2* vp = (const u32x2*)(V + (size_t)(half ? eb : ea) * 768 + 24 * c32); vw[r][0] = vp[0]; vw[r][1] = vp[1]; vw[r][2] = vp[2]; }
;             float d0 = 0.f, d1 = 0.f, d2 = 0.f, d3 = 0.f;
;             {   const v6u_t p0 = (v6u_t){u0.x, u0.y, u0.z, u0.w, u1.x, u1.y};
;                 const v32bf_t r0 = __builtin_amdgcn_cvt_scalef32_pk32_bf16_fp6(p0, 1.0f);
; #pragma unroll
;                 for (int k = 0; k < 16; k += 4) { d0 = dot2pb(r0[2 * k], r0[2 * k + 1], hf2[k], d0); d1 = dot2pb(r0[2 * k + 2], r0[2 * k + 3], hf2[k + 1], d1);
;                     d2 = dot2pb(r0[2 * k + 4], r0[2 * k + 5], hf2[k + 2], d2); d3 = dot2pb(r0[2 * k + 6], r0[2 * k + 7], hf2[k + 3], d3); } }
;             {   const v6u_t p1 = (v6u_t){u1.z, u1.w, u2.x, u2.y, u2.z, u2.w};
;                 const v32bf_t r1 = __builtin_amdgcn_cvt_scalef32_pk32_bf16_fp6(p1, 1.0f);
; #pragma unroll
;                 for (int k = 0; k < 16; k += 4) { d0 = dot2pb(r1[2 * k], r1[2 * k + 1], hf2[16 + k], d0); d1 = dot2pb(r1[2 * k + 2], r1[2 * k + 3], hf2[16 + k + 1], d1);
;                     d2 = dot2pb(r1[2 * k + 4], r1[2 * k + 5], hf2[16 + k + 2], d2); d3 = dot2pb(r1[2 * k + 6], r1[2 * k + 7], hf2[16 + k + 3], d3); } }
;             const float d = row16_sum((d0 + d1) + (d2 + d3)) * FP6_INV;
;             const float a = gt * gelu1(d) * FP6_INV;
	v_mad_u32_u24 v0, v58, s14, v92
	global_load_dwordx4 v[44:47], v0, s[46:47]
	global_load_dwordx4 v[48:51], v0, s[46:47] offset:16
	global_load_dwordx4 v[52:55], v0, s[46:47] offset:32
	s_waitcnt vmcnt(3)
	v_cvt_scalef32_pk32_bf16_fp6 v[0:15], v[32:37], 1.0
	v_dot2_f32_bf16 v23, v0, v95, 0
	v_dot2_f32_bf16 v25, v1, v159, 0
	v_dot2_f32_bf16 v22, v2, v160, 0
	v_dot2_f32_bf16 v24, v3, v161, 0
	v_dot2c_f32_bf16_e32 v23, v4, v180
	v_dot2c_f32_bf16_e32 v25, v5, v181
	v_dot2c_f32_bf16_e32 v22, v6, v182
	v_dot2c_f32_bf16_e32 v24, v7, v183
	v_dot2c_f32_bf16_e32 v23, v8, v184
	v_dot2c_f32_bf16_e32 v25, v9, v185
	v_dot2c_f32_bf16_e32 v22, v10, v186
	v_dot2c_f32_bf16_e32 v24, v11, v187
	v_dot2c_f32_bf16_e32 v23, v12, v188
	v_dot2c_f32_bf16_e32 v25, v13, v189
	v_dot2c_f32_bf16_e32 v22, v14, v190
	v_dot2c_f32_bf16_e32 v24, v15, v191
	v_cvt_scalef32_pk32_bf16_fp6 v[0:15], v[38:43], 1.0
	v_dot2c_f32_bf16_e32 v23, v0, v192
	v_dot2c_f32_bf16_e32 v25, v1, v193
	v_dot2c_f32_bf16_e32 v22, v2, v194
	v_dot2c_f32_bf16_e32 v24, v3, v195
	v_dot2c_f32_bf16_e32 v23, v4, v196
	v_dot2c_f32_bf16_e32 v25, v5, v197
	v_dot2c_f32_bf16_e32 v22, v6, v198
	v_dot2c_f32_bf16_e32 v24, v7, v199
	v_dot2c_f32_bf16_e32 v23, v8, v200
	v_dot2c_f32_bf16_e32 v25, v9, v201
	v_dot2c_f32_bf16_e32 v22, v10, v202
	v_dot2c_f32_bf16_e32 v24, v11, v203
	v_dot2c_f32_bf16_e32 v23, v12, v204
	v_dot2c_f32_bf16_e32 v25, v13, v205
	v_dot2c_f32_bf16_e32 v22, v14, v206
	v_dot2c_f32_bf16_e32 v24, v15, v207
	s_nop 2
	v_pk_add_f32 v[0:1], v[24:25], v[22:23]
	s_nop 0
	v_add_f32_e32 v249, v0, v1
	v_add_u32_e32 v62, v61, v155
	ds_read_b32 v209, v62 offset:448
	v_cndmask_b32_e64 v2, v247, v246, s[58:59]
	v_cndmask_b32_e64 v3, v246, v247, s[58:59]
	v_cndmask_b32_e64 v4, v249, v248, s[58:59]
	v_cndmask_b32_e64 v5, v248, v249, s[58:59]
	v_add_f32_dpp v3, v2, v3 quad_perm:[1,0,3,2] row_mask:0xf bank_mask:0xf bound_ctrl:1
	v_add_f32_dpp v5, v4, v5 quad_perm:[1,0,3,2] row_mask:0xf bank_mask:0xf bound_ctrl:1
	v_cndmask_b32_e64 v2, v5, v3, s[60:61]
	v_cndmask_b32_e64 v0, v3, v5, s[60:61]
	s_nop 0
	v_add_f32_dpp v0, v2, v0 quad_perm:[2,3,0,1] row_mask:0xf bank_mask:0xf bound_ctrl:1
	s_nop 1
	v_add_f32_dpp v0, v0, v0 row_ror:4 row_mask:0xf bank_mask:0xf bound_ctrl:1
	s_nop 1
	v_add_f32_dpp v0, v0, v0 row_ror:8 row_mask:0xf bank_mask:0xf bound_ctrl:1
	v_mul_f32_e32 v0, 0x3caaaaab, v0
	v_and_b32_e32 v2, 0x7fffffff, v0
	v_pk_fma_f32 v[2:3], v[2:3], s[16:17], 1.0 op_sel_hi:[0,0,0]
	v_rcp_f32_e32 v2, v2
	v_rcp_f32_e32 v3, v3
	v_mul_f32_e32 v1, v0, v0
	v_mul_f32_e32 v1, 0xbf38aa3b, v1
	v_cmp_gt_f32_e32 vcc, 0, v0
	v_pk_fma_f32 v[4:5], v[2:3], s[24:25], v[130:131] op_sel_hi:[1,0,0]
	s_nop 0
	v_pk_fma_f32 v[4:5], v[2:3], v[4:5], s[28:29] op_sel_hi:[1,1,0]
	s_nop 0
	v_pk_fma_f32 v[4:5], v[2:3], v[4:5], s[30:31] op_sel_hi:[1,1,0]
	s_nop 0
	v_pk_fma_f32 v[4:5], v[2:3], v[4:5], s[36:37] op_sel_hi:[1,1,0]
	s_nop 0
	v_pk_mul_f32 v[2:3], v[2:3], v[4:5]
	v_exp_f32_e32 v4, v1
	s_nop 0
	v_pk_mul_f32 v[2:3], v[4:5], v[2:3] op_sel_hi:[0,1]
	v_pk_fma_f32 v[4:5], v[0:1], v[2:3], v[0:1] op_sel_hi:[0,1,1] neg_lo:[1,0,0] neg_hi:[1,0,0]
	v_mul_f32_e32 v0, v0, v2
	v_cndmask_b32_e32 v0, v4, v0, vcc
	s_waitcnt lgkmcnt(0)
	v_mul_f32_e32 v0, v0, v209
	v_mul_f32_e32 v60, 0x3caaaaab, v0
	ds_write_b32 v62, v60 offset:960
	ds_read_b32 v56, v61
	v_add_u32_e32 v61, 16, v61
	s_add_i32 s1, s1, 1
	s_waitcnt lgkmcnt(0)
	v_mad_u32_u24 v0, v56, s14, v92
	global_load_dwordx4 v[32:35], v0, s[46:47]
	global_load_dwordx4 v[36:39], v0, s[46:47] offset:16
	global_load_dwordx4 v[40:43], v0, s[46:47] offset:32
	s_waitcnt vmcnt(3)
	v_cvt_scalef32_pk32_bf16_fp6 v[0:15], v[44:49], 1.0
	v_dot2_f32_bf16 v23, v0, v212, 0
	v_dot2_f32_bf16 v25, v1, v213, 0
	v_dot2_f32_bf16 v22, v2, v214, 0
	v_dot2_f32_bf16 v24, v3, v215, 0
	v_dot2c_f32_bf16_e32 v23, v4, v218
	v_dot2c_f32_bf16_e32 v25, v5, v219
	v_dot2c_f32_bf16_e32 v22, v6, v220
	v_dot2c_f32_bf16_e32 v24, v7, v221
	v_dot2c_f32_bf16_e32 v23, v8, v222
	v_dot2c_f32_bf16_e32 v25, v9, v223
	v_dot2c_f32_bf16_e32 v22, v10, v224
	v_dot2c_f32_bf16_e32 v24, v11, v225
	v_dot2c_f32_bf16_e32 v23, v12, v226
	v_dot2c_f32_bf16_e32 v25, v13, v227
	v_dot2c_f32_bf16_e32 v22, v14, v228
	v_dot2c_f32_bf16_e32 v24, v15, v229
	v_cvt_scalef32_pk32_bf16_fp6 v[0:15], v[50:55], 1.0
	v_dot2c_f32_bf16_e32 v23, v0, v230
	v_dot2c_f32_bf16_e32 v25, v1, v231
	v_dot2c_f32_bf16_e32 v22, v2, v232
	v_dot2c_f32_bf16_e32 v24, v3, v233
	v_dot2c_f32_bf16_e32 v23, v4, v234
	v_dot2c_f32_bf16_e32 v25, v5, v235
	v_dot2c_f32_bf16_e32 v22, v6, v236
	v_dot2c_f32_bf16_e32 v24, v7, v237
	v_dot2c_f32_bf16_e32 v23, v8, v238
	v_dot2c_f32_bf16_e32 v25, v9, v239
	v_dot2c_f32_bf16_e32 v22, v10, v240
	v_dot2c_f32_bf16_e32 v24, v11, v241
	v_dot2c_f32_bf16_e32 v23, v12, v242
	v_dot2c_f32_bf16_e32 v25, v13, v243
	v_dot2c_f32_bf16_e32 v22, v14, v244
	v_dot2c_f32_bf16_e32 v24, v15, v245
	s_nop 2
	v_pk_add_f32 v[0:1], v[24:25], v[22:23]
	s_nop 0
	v_add_f32_e32 v63, v0, v1
	v_add_u32_e32 v62, v61, v155
	ds_read_b32 v211, v62 offset:1968
	v_cndmask_b32_e64 v2, v216, v250, s[58:59]
	v_cndmask_b32_e64 v3, v250, v216, s[58:59]
	v_cndmask_b32_e64 v4, v63, v217, s[58:59]
	v_cndmask_b32_e64 v5, v217, v63, s[58:59]
	v_add_f32_dpp v3, v2, v3 quad_perm:[1,0,3,2] row_mask:0xf bank_mask:0xf bound_ctrl:1
	v_add_f32_dpp v5, v4, v5 quad_perm:[1,0,3,2] row_mask:0xf bank_mask:0xf bound_ctrl:1
	v_cndmask_b32_e64 v2, v5, v3, s[60:61]
	v_cndmask_b32_e64 v0, v3, v5, s[60:61]
	s_nop 0
	v_add_f32_dpp v0, v2, v0 quad_perm:[2,3,0,1] row_mask:0xf bank_mask:0xf bound_ctrl:1
	s_nop 1
	v_add_f32_dpp v0, v0, v0 row_ror:4 row_mask:0xf bank_mask:0xf bound_ctrl:1
	s_nop 1
	v_add_f32_dpp v0, v0, v0 row_ror:8 row_mask:0xf bank_mask:0xf bound_ctrl:1
	v_mul_f32_e32 v0, 0x3caaaaab, v0
	v_and_b32_e32 v2, 0x7fffffff, v0
	v_pk_fma_f32 v[2:3], v[2:3], s[16:17], 1.0 op_sel_hi:[0,0,0]
	v_rcp_f32_e32 v2, v2
	v_rcp_f32_e32 v3, v3
	v_mul_f32_e32 v1, v0, v0
	v_mul_f32_e32 v1, 0xbf38aa3b, v1
	v_cmp_gt_f32_e32 vcc, 0, v0
	v_pk_fma_f32 v[4:5], v[2:3], s[24:25], v[130:131] op_sel_hi:[1,0,0]
	s_nop 0
	v_pk_fma_f32 v[4:5], v[2:3], v[4:5], s[28:29] op_sel_hi:[1,1,0]
	s_nop 0
	v_pk_fma_f32 v[4:5], v[2:3], v[4:5], s[30:31] op_sel_hi:[1,1,0]
	s_nop 0
	v_pk_fma_f32 v[4:5], v[2:3], v[4:5], s[36:37] op_sel_hi:[1,1,0]
	s_nop 0
	v_pk_mul_f32 v[2:3], v[2:3], v[4:5]
	v_exp_f32_e32 v4, v1
	s_nop 0
	v_pk_mul_f32 v[2:3], v[4:5], v[2:3] op_sel_hi:[0,1]
	v_pk_fma_f32 v[4:5], v[0:1], v[2:3], v[0:1] op_sel_hi:[0,1,1] neg_lo:[1,0,0] neg_hi:[1,0,0]
	v_mul_f32_e32 v0, v0, v2
	v_cndmask_b32_e32 v0, v4, v0, vcc
	s_waitcnt lgkmcnt(0)
	v_mul_f32_e32 v0, v0, v211
	v_mul_f32_e32 v60, 0x3caaaaab, v0
	ds_write_b32 v62, v60 offset:2480
	s_cmp_lt_u32 s1, 29
	s_cbranch_scc1 .Lpeer_uloop
; __device__ __forceinline__ float gelu1(float v) { const f32x2 r = gelu_pk((f32x2){v, v}); return r.x; }
; __device__ void ph_peer(const float* __restrict__ SC, const bf16_t* __restrict__ H  , const float* __restrict__ gffn, const unsigned char* __restrict__ U, const unsigned char* __restrict__ V, float* X, const float* __restrict__ fgain) {
;     ...
;         for (int it = 0; it < 32; ++it) {
;             const int src = (it * 4 + grp) & 63;
;             const int e = __shfl(it < 16 ? idx_lo : idx_hi, src);
;             const float gt = __shfl(it < 16 ? g_lo : g_hi, src);
;             const u32x4* up = (const u32x4*)(U + (size_t)e * 768 + 48 * sub);
;             const u32x4 u0 = up[0], u1 = up[1], u2 = up[2];
;             u32x2 vw[2][3];
; #pragma unroll
;             for (int r = 0; r < 2; ++r) { const int ea = __builtin_amdgcn_readlane(e, 32 * r), eb = __builtin_amdgcn_readlane(e, 32 * r + 16);
;                 const u32x2* vp = (const u32x2*)(V + (size_t)(half ? eb : ea) * 768 + 24 * c32); vw[r][0] = vp[0]; vw[r][1] = vp[1]; vw[r][2] = vp[2]; }
;             float d0 = 0.f, d1 = 0.f, d2 = 0.f, d3 = 0.f;
;             {   const v6u_t p0 = (v6u_t){u0.x, u0.y, u0.z, u0.w, u1.x, u1.y};
;                 const v32bf_t r0 = __builtin_amdgcn_cvt_scalef32_pk32_bf16_fp6(p0, 1.0f);
; #pragma unroll
;                 for (int k = 0; k < 16; k += 4) { d0 = dot2pb(r0[2 * k], r0[2 * k + 1], hf2[k], d0); d1 = dot2pb(r0[2 * k + 2], r0[2 * k + 3], hf2[k + 1], d1);
;                     d2 = dot2pb(r0[2 * k + 4], r0[2 * k + 5], hf2[k + 2], d2); d3 = dot2pb(r0[2 * k + 6], r0[2 * k + 7], hf2[k + 3], d3); } }
;             {   const v6u_t p1 = (v6u_t){u1.z, u1.w, u2.x, u2.y, u2.z, u2.w};
;                 const v32bf_t r1 = __builtin_amdgcn_cvt_scalef32_pk32_bf16_fp6(p1, 1.0f);
; #pragma unroll
;                 for (int k = 0; k < 16; k += 4) { d0 = dot2pb(r1[2 * k], r1[2 * k + 1], hf2[16 + k], d0); d1 = dot2pb(r1[2 * k + 2], r1[2 * k + 3], hf2[16 + k + 1], d1);
;                     d2 = dot2pb(r1[2 * k + 4], r1[2 * k + 5], hf2[16 + k + 2], d2); d3 = dot2pb(r1[2 * k + 6], r1[2 * k + 7], hf2[16 + k + 3], d3); } }
;             const float d = row16_sum((d0 + d1) + (d2 + d3)) * FP6_INV;
;             const float a = gt * gelu1(d) * FP6_INV;
	ds_read_b32 v58, v61 offset:1520
	s_waitcnt lgkmcnt(0)
	v_mad_u32_u24 v0, v58, s14, v92
	global_load_dwordx4 v[44:47], v0, s[46:47]
	global_load_dwordx4 v[48:51], v0, s[46:47] offset:16
	global_load_dwordx4 v[52:55], v0, s[46:47] offset:32
	s_waitcnt vmcnt(3)
	v_cvt_scalef32_pk32_bf16_fp6 v[0:15], v[32:37], 1.0
	v_dot2_f32_bf16 v23, v0, v95, 0
	v_dot2_f32_bf16 v25, v1, v159, 0
	v_dot2_f32_bf16 v22, v2, v160, 0
	v_dot2_f32_bf16 v24, v3, v161, 0
	v_dot2c_f32_bf16_e32 v23, v4, v180
	v_dot2c_f32_bf16_e32 v25, v5, v181
	v_dot2c_f32_bf16_e32 v22, v6, v182
	v_dot2c_f32_bf16_e32 v24, v7, v183
	v_dot2c_f32_bf16_e32 v23, v8, v184
	v_dot2c_f32_bf16_e32 v25, v9, v185
	v_dot2c_f32_bf16_e32 v22, v10, v186
	v_dot2c_f32_bf16_e32 v24, v11, v187
	v_dot2c_f32_bf16_e32 v23, v12, v188
	v_dot2c_f32_bf16_e32 v25, v13, v189
	v_dot2c_f32_bf16_e32 v22, v14, v190
	v_dot2c_f32_bf16_e32 v24, v15, v191
	v_cvt_scalef32_pk32_bf16_fp6 v[0:15], v[38:43], 1.0
	v_dot2c_f32_bf16_e32 v23, v0, v192
	v_dot2c_f32_bf16_e32 v25, v1, v193
	v_dot2c_f32_bf16_e32 v22, v2, v194
	v_dot2c_f32_bf16_e32 v24, v3, v195
	v_dot2c_f32_bf16_e32 v23, v4, v196
	v_dot2c_f32_bf16_e32 v25, v5, v197
	v_dot2c_f32_bf16_e32 v22, v6, v198
	v_dot2c_f32_bf16_e32 v24, v7, v199
	v_dot2c_f32_bf16_e32 v23, v8, v200
	v_dot2c_f32_bf16_e32 v25, v9, v201
	v_dot2c_f32_bf16_e32 v22, v10, v202
	v_dot2c_f32_bf16_e32 v24, v11, v203
	v_dot2c_f32_bf16_e32 v23, v12, v204
	v_dot2c_f32_bf16_e32 v25, v13, v205
	v_dot2c_f32_bf16_e32 v22, v14, v206
	v_dot2c_f32_bf16_e32 v24, v15, v207
	s_nop 2
	v_pk_add_f32 v[0:1], v[24:25], v[22:23]
	s_nop 0
	v_add_f32_e32 v246, v0, v1
	ds_read_b32 v56, v61
	v_add_u32_e32 v61, 16, v61
	s_add_i32 s1, s1, 1
	s_waitcnt lgkmcnt(0)
	v_mad_u32_u24 v0, v56, s14, v92
	global_load_dwordx4 v[32:35], v0, s[46:47]
	global_load_dwordx4 v[36:39], v0, s[46:47] offset:16
	global_load_dwordx4 v[40:43], v0, s[46:47] offset:32
	s_waitcnt vmcnt(3)
	v_cvt_scalef32_pk32_bf16_fp6 v[0:15], v[44:49], 1.0
	v_dot2_f32_bf16 v23, v0, v212, 0
	v_dot2_f32_bf16 v25, v1, v213, 0
	v_dot2_f32_bf16 v22, v2, v214, 0
	v_dot2_f32_bf16 v24, v3, v215, 0
	v_dot2c_f32_bf16_e32 v23, v4, v218
	v_dot2c_f32_bf16_e32 v25, v5, v219
	v_dot2c_f32_bf16_e32 v22, v6, v220
	v_dot2c_f32_bf16_e32 v24, v7, v221
	v_dot2c_f32_bf16_e32 v23, v8, v222
	v_dot2c_f32_bf16_e32 v25, v9, v223
	v_dot2c_f32_bf16_e32 v22, v10, v224
	v_dot2c_f32_bf16_e32 v24, v11, v225
	v_dot2c_f32_bf16_e32 v23, v12, v226
	v_dot2c_f32_bf16_e32 v25, v13, v227
	v_dot2c_f32_bf16_e32 v22, v14, v228
	v_dot2c_f32_bf16_e32 v24, v15, v229
	v_cvt_scalef32_pk32_bf16_fp6 v[0:15], v[50:55], 1.0
	v_dot2c_f32_bf16_e32 v23, v0, v230
	v_dot2c_f32_bf16_e32 v25, v1, v231
	v_dot2c_f32_bf16_e32 v22, v2, v232
	v_dot2c_f32_bf16_e32 v24, v3, v233
	v_dot2c_f32_bf16_e32 v23, v4, v234
	v_dot2c_f32_bf16_e32 v25, v5, v235
	v_dot2c_f32_bf16_e32 v22, v6, v236
	v_dot2c_f32_bf16_e32 v24, v7, v237
	v_dot2c_f32_bf16_e32 v23, v8, v238
	v_dot2c_f32_bf16_e32 v25, v9, v239
	v_dot2c_f32_bf16_e32 v22, v10, v240
	v_dot2c_f32_bf16_e32 v24, v11, v241
	v_dot2c_f32_bf16_e32 v23, v12, v242
	v_dot2c_f32_bf16_e32 v25, v13, v243
	v_dot2c_f32_bf16_e32 v22, v14, v244
	v_dot2c_f32_bf16_e32 v24, v15, v245
	s_nop 2
	v_pk_add_f32 v[0:1], v[24:25], v[22:23]
	s_nop 0
	v_add_f32_e32 v250, v0, v1
	ds_read_b32 v58, v61 offset:1520
	s_waitcnt lgkmcnt(0)
	v_mad_u32_u24 v0, v58, s14, v92
	global_load_dwordx4 v[44:47], v0, s[46:47]
	global_load_dwordx4 v[48:51], v0, s[46:47] offset:16
	global_load_dwordx4 v[52:55], v0, s[46:47] offset:32
	s_waitcnt vmcnt(3)
	v_cvt_scalef32_pk32_bf16_fp6 v[0:15], v[32:37], 1.0
	v_dot2_f32_bf16 v23, v0, v95, 0
	v_dot2_f32_bf16 v25, v1, v159, 0
	v_dot2_f32_bf16 v22, v2, v160, 0
	v_dot2_f32_bf16 v24, v3, v161, 0
	v_dot2c_f32_bf16_e32 v23, v4, v180
	v_dot2c_f32_bf16_e32 v25, v5, v181
	v_dot2c_f32_bf16_e32 v22, v6, v182
	v_dot2c_f32_bf16_e32 v24, v7, v183
	v_dot2c_f32_bf16_e32 v23, v8, v184
	v_dot2c_f32_bf16_e32 v25, v9, v185
	v_dot2c_f32_bf16_e32 v22, v10, v186
	v_dot2c_f32_bf16_e32 v24, v11, v187
	v_dot2c_f32_bf16_e32 v23, v12, v188
	v_dot2c_f32_bf16_e32 v25, v13, v189
	v_dot2c_f32_bf16_e32 v22, v14, v190
	v_dot2c_f32_bf16_e32 v24, v15, v191
	v_cvt_scalef32_pk32_bf16_fp6 v[0:15], v[38:43], 1.0
	v_dot2c_f32_bf16_e32 v23, v0, v192
	v_dot2c_f32_bf16_e32 v25, v1, v193
	v_dot2c_f32_bf16_e32 v22, v2, v194
	v_dot2c_f32_bf16_e32 v24, v3, v195
	v_dot2c_f32_bf16_e32 v23, v4, v196
	v_dot2c_f32_bf16_e32 v25, v5, v197
	v_dot2c_f32_bf16_e32 v22, v6, v198
	v_dot2c_f32_bf16_e32 v24, v7, v199
	v_dot2c_f32_bf16_e32 v23, v8, v200
	v_dot2c_f32_bf16_e32 v25, v9, v201
	v_dot2c_f32_bf16_e32 v22, v10, v202
	v_dot2c_f32_bf16_e32 v24, v11, v203
	v_dot2c_f32_bf16_e32 v23, v12, v204
	v_dot2c_f32_bf16_e32 v25, v13, v205
	v_dot2c_f32_bf16_e32 v22, v14, v206
	v_dot2c_f32_bf16_e32 v24, v15, v207
	s_nop 2
	v_pk_add_f32 v[0:1], v[24:25], v[22:23]
	s_nop 0
	v_add_f32_e32 v247, v0, v1
	ds_read_b32 v56, v61
	v_add_u32_e32 v61, 16, v61
	s_add_i32 s1, s1, 1
	s_waitcnt lgkmcnt(0)
	v_mad_u32_u24 v0, v56, s14, v92
	global_load_dwordx4 v[32:35], v0, s[46:47]
	global_load_dwordx4 v[36:39], v0, s[46:47] offset:16
	global_load_dwordx4 v[40:43], v0, s[46:47] offset:32
	s_waitcnt vmcnt(3)
; __device__ __forceinline__ float gelu1(float v) { const f32x2 r = gelu_pk((f32x2){v, v}); return r.x; }
; __device__ void ph_peer(const float* __restrict__ SC, const bf16_t* __restrict__ H  , const float* __restrict__ gffn, const unsigned char* __restrict__ U, const unsigned char* __restrict__ V, float* X, const float* __restrict__ fgain) {
;     ...
;         for (int it = 0; it < 32; ++it) {
;             const int src = (it * 4 + grp) & 63;
;             const int e = __shfl(it < 16 ? idx_lo : idx_hi, src);
;             const float gt = __shfl(it < 16 ? g_lo : g_hi, src);
;             const u32x4* up = (const u32x4*)(U + (size_t)e * 768 + 48 * sub);
;             const u32x4 u0 = up[0], u1 = up[1], u2 = up[2];
;             u32x2 vw[2][3];
; #pragma unroll
;             for (int r = 0; r < 2; ++r) { const int ea = __builtin_amdgcn_readlane(e, 32 * r), eb = __builtin_amdgcn_readlane(e, 32 * r + 16);
;                 const u32x2* vp = (const u32x2*)(V + (size_t)(half ? eb : ea) * 768 + 24 * c32); vw[r][0] = vp[0]; vw[r][1] = vp[1]; vw[r][2] = vp[2]; }
;             float d0 = 0.f, d1 = 0.f, d2 = 0.f, d3 = 0.f;
;             {   const v6u_t p0 = (v6u_t){u0.x, u0.y, u0.z, u0.w, u1.x, u1.y};
;                 const v32bf_t r0 = __builtin_amdgcn_cvt_scalef32_pk32_bf16_fp6(p0, 1.0f);
; #pragma unroll
;                 for (int k = 0; k < 16; k += 4) { d0 = dot2pb(r0[2 * k], r0[2 * k + 1], hf2[k], d0); d1 = dot2pb(r0[2 * k + 2], r0[2 * k + 3], hf2[k + 1], d1);
;                     d2 = dot2pb(r0[2 * k + 4], r0[2 * k + 5], hf2[k + 2], d2); d3 = dot2pb(r0[2 * k + 6], r0[2 * k + 7], hf2[k + 3], d3); } }
;             {   const v6u_t p1 = (v6u_t){u1.z, u1.w, u2.x, u2.y, u2.z, u2.w};
;                 const v32bf_t r1 = __builtin_amdgcn_cvt_scalef32_pk32_bf16_fp6(p1, 1.0f);
; #pragma unroll
;                 for (int k = 0; k < 16; k += 4) { d0 = dot2pb(r1[2 * k], r1[2 * k + 1], hf2[16 + k], d0); d1 = dot2pb(r1[2 * k + 2], r1[2 * k + 3], hf2[16 + k + 1], d1);
;                     d2 = dot2pb(r1[2 * k + 4], r1[2 * k + 5], hf2[16 + k + 2], d2); d3 = dot2pb(r1[2 * k + 6], r1[2 * k + 7], hf2[16 + k + 3], d3); } }
;             const float d = row16_sum((d0 + d1) + (d2 + d3)) * FP6_INV;
;             const float a = gt * gelu1(d) * FP6_INV;
	v_cvt_scalef32_pk32_bf16_fp6 v[0:15], v[44:49], 1.0
	v_dot2_f32_bf16 v23, v0, v212, 0
	v_dot2_f32_bf16 v25, v1, v213, 0
	v_dot2_f32_bf16 v22, v2, v214, 0
	v_dot2_f32_bf16 v24, v3, v215, 0
	v_dot2c_f32_bf16_e32 v23, v4, v218
	v_dot2c_f32_bf16_e32 v25, v5, v219
	v_dot2c_f32_bf16_e32 v22, v6, v220
	v_dot2c_f32_bf16_e32 v24, v7, v221
	v_dot2c_f32_bf16_e32 v23, v8, v222
	v_dot2c_f32_bf16_e32 v25, v9, v223
	v_dot2c_f32_bf16_e32 v22, v10, v224
	v_dot2c_f32_bf16_e32 v24, v11, v225
	v_dot2c_f32_bf16_e32 v23, v12, v226
	v_dot2c_f32_bf16_e32 v25, v13, v227
	v_dot2c_f32_bf16_e32 v22, v14, v228
	v_dot2c_f32_bf16_e32 v24, v15, v229
	v_cvt_scalef32_pk32_bf16_fp6 v[0:15], v[50:55], 1.0
	v_dot2c_f32_bf16_e32 v23, v0, v230
	v_dot2c_f32_bf16_e32 v25, v1, v231
	v_dot2c_f32_bf16_e32 v22, v2, v232
	v_dot2c_f32_bf16_e32 v24, v3, v233
	v_dot2c_f32_bf16_e32 v23, v4, v234
	v_dot2c_f32_bf16_e32 v25, v5, v235
	v_dot2c_f32_bf16_e32 v22, v6, v236
	v_dot2c_f32_bf16_e32 v24, v7, v237
	v_dot2c_f32_bf16_e32 v23, v8, v238
	v_dot2c_f32_bf16_e32 v25, v9, v239
	v_dot2c_f32_bf16_e32 v22, v10, v240
	v_dot2c_f32_bf16_e32 v24, v11, v241
	v_dot2c_f32_bf16_e32 v23, v12, v242
	v_dot2c_f32_bf16_e32 v25, v13, v243
	v_dot2c_f32_bf16_e32 v22, v14, v244
	v_dot2c_f32_bf16_e32 v24, v15, v245
	s_nop 2
	v_pk_add_f32 v[0:1], v[24:25], v[22:23]
	s_nop 0
	v_add_f32_e32 v216, v0, v1
	ds_read_b32 v58, v61 offset:1520
	s_waitcnt lgkmcnt(0)
	v_mad_u32_u24 v0, v58, s14, v92
	global_load_dwordx4 v[44:47], v0, s[46:47]
	global_load_dwordx4 v[48:51], v0, s[46:47] offset:16
	global_load_dwordx4 v[52:55], v0, s[46:47] offset:32
	s_waitcnt vmcnt(3)
	v_cvt_scalef32_pk32_bf16_fp6 v[0:15], v[32:37], 1.0
	v_dot2_f32_bf16 v23, v0, v95, 0
	v_dot2_f32_bf16 v25, v1, v159, 0
	v_dot2_f32_bf16 v22, v2, v160, 0
	v_dot2_f32_bf16 v24, v3, v161, 0
	v_dot2c_f32_bf16_e32 v23, v4, v180
	v_dot2c_f32_bf16_e32 v25, v5, v181
	v_dot2c_f32_bf16_e32 v22, v6, v182
	v_dot2c_f32_bf16_e32 v24, v7, v183
	v_dot2c_f32_bf16_e32 v23, v8, v184
	v_dot2c_f32_bf16_e32 v25, v9, v185
	v_dot2c_f32_bf16_e32 v22, v10, v186
	v_dot2c_f32_bf16_e32 v24, v11, v187
	v_dot2c_f32_bf16_e32 v23, v12, v188
	v_dot2c_f32_bf16_e32 v25, v13, v189
	v_dot2c_f32_bf16_e32 v22, v14, v190
	v_dot2c_f32_bf16_e32 v24, v15, v191
	v_cvt_scalef32_pk32_bf16_fp6 v[0:15], v[38:43], 1.0
	v_dot2c_f32_bf16_e32 v23, v0, v192
	v_dot2c_f32_bf16_e32 v25, v1, v193
	v_dot2c_f32_bf16_e32 v22, v2, v194
	v_dot2c_f32_bf16_e32 v24, v3, v195
	v_dot2c_f32_bf16_e32 v23, v4, v196
	v_dot2c_f32_bf16_e32 v25, v5, v197
	v_dot2c_f32_bf16_e32 v22, v6, v198
	v_dot2c_f32_bf16_e32 v24, v7, v199
	v_dot2c_f32_bf16_e32 v23, v8, v200
	v_dot2c_f32_bf16_e32 v25, v9, v201
	v_dot2c_f32_bf16_e32 v22, v10, v202
	v_dot2c_f32_bf16_e32 v24, v11, v203
	v_dot2c_f32_bf16_e32 v23, v12, v204
	v_dot2c_f32_bf16_e32 v25, v13, v205
	v_dot2c_f32_bf16_e32 v22, v14, v206
	v_dot2c_f32_bf16_e32 v24, v15, v207
	s_nop 2
	v_pk_add_f32 v[0:1], v[24:25], v[22:23]
	s_nop 0
	v_add_f32_e32 v248, v0, v1
	ds_read_b32 v56, v61
	v_add_u32_e32 v61, 16, v61
	s_add_i32 s1, s1, 1
	s_waitcnt lgkmcnt(0)
	v_mad_u32_u24 v0, v56, s14, v92
	global_load_dwordx4 v[32:35], v0, s[46:47]
	global_load_dwordx4 v[36:39], v0, s[46:47] offset:16
	global_load_dwordx4 v[40:43], v0, s[46:47] offset:32
	s_waitcnt vmcnt(3)
	v_cvt_scalef32_pk32_bf16_fp6 v[0:15], v[44:49], 1.0
	v_dot2_f32_bf16 v23, v0, v212, 0
	v_dot2_f32_bf16 v25, v1, v213, 0
	v_dot2_f32_bf16 v22, v2, v214, 0
	v_dot2_f32_bf16 v24, v3, v215, 0
	v_dot2c_f32_bf16_e32 v23, v4, v218
	v_dot2c_f32_bf16_e32 v25, v5, v219
	v_dot2c_f32_bf16_e32 v22, v6, v220
	v_dot2c_f32_bf16_e32 v24, v7, v221
	v_dot2c_f32_bf16_e32 v23, v8, v222
	v_dot2c_f32_bf16_e32 v25, v9, v223
	v_dot2c_f32_bf16_e32 v22, v10, v224
	v_dot2c_f32_bf16_e32 v24, v11, v225
	v_dot2c_f32_bf16_e32 v23, v12, v226
	v_dot2c_f32_bf16_e32 v25, v13, v227
	v_dot2c_f32_bf16_e32 v22, v14, v228
	v_dot2c_f32_bf16_e32 v24, v15, v229
	v_cvt_scalef32_pk32_bf16_fp6 v[0:15], v[50:55], 1.0
	v_dot2c_f32_bf16_e32 v23, v0, v230
	v_dot2c_f32_bf16_e32 v25, v1, v231
	v_dot2c_f32_bf16_e32 v22, v2, v232
	v_dot2c_f32_bf16_e32 v24, v3, v233
	v_dot2c_f32_bf16_e32 v23, v4, v234
	v_dot2c_f32_bf16_e32 v25, v5, v235
	v_dot2c_f32_bf16_e32 v22, v6, v236
	v_dot2c_f32_bf16_e32 v24, v7, v237
	v_dot2c_f32_bf16_e32 v23, v8, v238
	v_dot2c_f32_bf16_e32 v25, v9, v239
	v_dot2c_f32_bf16_e32 v22, v10, v240
	v_dot2c_f32_bf16_e32 v24, v11, v241
	v_dot2c_f32_bf16_e32 v23, v12, v242
	v_dot2c_f32_bf16_e32 v25, v13, v243
	v_dot2c_f32_bf16_e32 v22, v14, v244
	v_dot2c_f32_bf16_e32 v24, v15, v245
	s_nop 2
	v_pk_add_f32 v[0:1], v[24:25], v[22:23]
	s_nop 0
	v_add_f32_e32 v217, v0, v1
	ds_read_b32 v58, v61 offset:1520
	s_waitcnt lgkmcnt(0)
	v_mad_u32_u24 v0, v58, s14, v92
	global_load_dwordx4 v[44:47], v0, s[46:47]
	global_load_dwordx4 v[48:51], v0, s[46:47] offset:16
	global_load_dwordx4 v[52:55], v0, s[46:47] offset:32
	s_waitcnt vmcnt(3)
; __device__ __forceinline__ float gelu1(float v) { const f32x2 r = gelu_pk((f32x2){v, v}); return r.x; }
; __device__ void ph_peer(const float* __restrict__ SC, const bf16_t* __restrict__ H  , const float* __restrict__ gffn, const unsigned char* __restrict__ U, const unsigned char* __restrict__ V, float* X, const float* __restrict__ fgain) {
;     ...
;         float acc[32];
; #pragma unroll
;         for (int i = 0; i < 32; ++i) acc[i] = 0.f;
;     ...
;         for (int it = 0; it < 32; ++it) {
;             const int src = (it * 4 + grp) & 63;
;             const int e = __shfl(it < 16 ? idx_lo : idx_hi, src);
;             const float gt = __shfl(it < 16 ? g_lo : g_hi, src);
;             const u32x4* up = (const u32x4*)(U + (size_t)e * 768 + 48 * sub);
;             const u32x4 u0 = up[0], u1 = up[1], u2 = up[2];
;             u32x2 vw[2][3];
; #pragma unroll
;             for (int r = 0; r < 2; ++r) { const int ea = __builtin_amdgcn_readlane(e, 32 * r), eb = __builtin_amdgcn_readlane(e, 32 * r + 16);
;                 const u32x2* vp = (const u32x2*)(V + (size_t)(half ? eb : ea) * 768 + 24 * c32); vw[r][0] = vp[0]; vw[r][1] = vp[1]; vw[r][2] = vp[2]; }
;             float d0 = 0.f, d1 = 0.f, d2 = 0.f, d3 = 0.f;
;             {   const v6u_t p0 = (v6u_t){u0.x, u0.y, u0.z, u0.w, u1.x, u1.y};
;                 const v32bf_t r0 = __builtin_amdgcn_cvt_scalef32_pk32_bf16_fp6(p0, 1.0f);
; #pragma unroll
;                 for (int k = 0; k < 16; k += 4) { d0 = dot2pb(r0[2 * k], r0[2 * k + 1], hf2[k], d0); d1 = dot2pb(r0[2 * k + 2], r0[2 * k + 3], hf2[k + 1], d1);
;                     d2 = dot2pb(r0[2 * k + 4], r0[2 * k + 5], hf2[k + 2], d2); d3 = dot2pb(r0[2 * k + 6], r0[2 * k + 7], hf2[k + 3], d3); } }
;             {   const v6u_t p1 = (v6u_t){u1.z, u1.w, u2.x, u2.y, u2.z, u2.w};
;                 const v32bf_t r1 = __builtin_amdgcn_cvt_scalef32_pk32_bf16_fp6(p1, 1.0f);
; #pragma unroll
;                 for (int k = 0; k < 16; k += 4) { d0 = dot2pb(r1[2 * k], r1[2 * k + 1], hf2[16 + k], d0); d1 = dot2pb(r1[2 * k + 2], r1[2 * k + 3], hf2[16 + k + 1], d1);
;                     d2 = dot2pb(r1[2 * k + 4], r1[2 * k + 5], hf2[16 + k + 2], d2); d3 = dot2pb(r1[2 * k + 6], r1[2 * k + 7], hf2[16 + k + 3], d3); } }
;             const float d = row16_sum((d0 + d1) + (d2 + d3)) * FP6_INV;
;             const float a = gt * gelu1(d) * FP6_INV;
	v_cvt_scalef32_pk32_bf16_fp6 v[0:15], v[32:37], 1.0
	v_dot2_f32_bf16 v23, v0, v95, 0
	v_dot2_f32_bf16 v25, v1, v159, 0
	v_dot2_f32_bf16 v22, v2, v160, 0
	v_dot2_f32_bf16 v24, v3, v161, 0
	v_dot2c_f32_bf16_e32 v23, v4, v180
	v_dot2c_f32_bf16_e32 v25, v5, v181
	v_dot2c_f32_bf16_e32 v22, v6, v182
	v_dot2c_f32_bf16_e32 v24, v7, v183
	v_dot2c_f32_bf16_e32 v23, v8, v184
	v_dot2c_f32_bf16_e32 v25, v9, v185
	v_dot2c_f32_bf16_e32 v22, v10, v186
	v_dot2c_f32_bf16_e32 v24, v11, v187
	v_dot2c_f32_bf16_e32 v23, v12, v188
	v_dot2c_f32_bf16_e32 v25, v13, v189
	v_dot2c_f32_bf16_e32 v22, v14, v190
	v_dot2c_f32_bf16_e32 v24, v15, v191
	v_cvt_scalef32_pk32_bf16_fp6 v[0:15], v[38:43], 1.0
	v_dot2c_f32_bf16_e32 v23, v0, v192
	v_dot2c_f32_bf16_e32 v25, v1, v193
	v_dot2c_f32_bf16_e32 v22, v2, v194
	v_dot2c_f32_bf16_e32 v24, v3, v195
	v_dot2c_f32_bf16_e32 v23, v4, v196
	v_dot2c_f32_bf16_e32 v25, v5, v197
	v_dot2c_f32_bf16_e32 v22, v6, v198
	v_dot2c_f32_bf16_e32 v24, v7, v199
	v_dot2c_f32_bf16_e32 v23, v8, v200
	v_dot2c_f32_bf16_e32 v25, v9, v201
	v_dot2c_f32_bf16_e32 v22, v10, v202
	v_dot2c_f32_bf16_e32 v24, v11, v203
	v_dot2c_f32_bf16_e32 v23, v12, v204
	v_dot2c_f32_bf16_e32 v25, v13, v205
	v_dot2c_f32_bf16_e32 v22, v14, v206
	v_dot2c_f32_bf16_e32 v24, v15, v207
	s_nop 2
	v_pk_add_f32 v[0:1], v[24:25], v[22:23]
	s_nop 0
	v_add_f32_e32 v249, v0, v1
	v_add_u32_e32 v62, v61, v155
	ds_read_b32 v209, v62 offset:448
	v_cndmask_b32_e64 v2, v247, v246, s[58:59]
	v_cndmask_b32_e64 v3, v246, v247, s[58:59]
	v_cndmask_b32_e64 v4, v249, v248, s[58:59]
	v_cndmask_b32_e64 v5, v248, v249, s[58:59]
	v_add_f32_dpp v3, v2, v3 quad_perm:[1,0,3,2] row_mask:0xf bank_mask:0xf bound_ctrl:1
	v_add_f32_dpp v5, v4, v5 quad_perm:[1,0,3,2] row_mask:0xf bank_mask:0xf bound_ctrl:1
	v_cndmask_b32_e64 v2, v5, v3, s[60:61]
	v_cndmask_b32_e64 v0, v3, v5, s[60:61]
	s_nop 0
	v_add_f32_dpp v0, v2, v0 quad_perm:[2,3,0,1] row_mask:0xf bank_mask:0xf bound_ctrl:1
	s_nop 1
	v_add_f32_dpp v0, v0, v0 row_ror:4 row_mask:0xf bank_mask:0xf bound_ctrl:1
	s_nop 1
	v_add_f32_dpp v0, v0, v0 row_ror:8 row_mask:0xf bank_mask:0xf bound_ctrl:1
	v_mul_f32_e32 v0, 0x3caaaaab, v0
	v_and_b32_e32 v2, 0x7fffffff, v0
	v_pk_fma_f32 v[2:3], v[2:3], s[16:17], 1.0 op_sel_hi:[0,0,0]
	v_rcp_f32_e32 v2, v2
	v_rcp_f32_e32 v3, v3
	v_mul_f32_e32 v1, v0, v0
	v_mul_f32_e32 v1, 0xbf38aa3b, v1
	v_cmp_gt_f32_e32 vcc, 0, v0
	v_pk_fma_f32 v[4:5], v[2:3], s[24:25], v[130:131] op_sel_hi:[1,0,0]
	s_nop 0
	v_pk_fma_f32 v[4:5], v[2:3], v[4:5], s[28:29] op_sel_hi:[1,1,0]
	s_nop 0
	v_pk_fma_f32 v[4:5], v[2:3], v[4:5], s[30:31] op_sel_hi:[1,1,0]
	s_nop 0
	v_pk_fma_f32 v[4:5], v[2:3], v[4:5], s[36:37] op_sel_hi:[1,1,0]
	s_nop 0
	v_pk_mul_f32 v[2:3], v[2:3], v[4:5]
	v_exp_f32_e32 v4, v1
	s_nop 0
	v_pk_mul_f32 v[2:3], v[4:5], v[2:3] op_sel_hi:[0,1]
	v_pk_fma_f32 v[4:5], v[0:1], v[2:3], v[0:1] op_sel_hi:[0,1,1] neg_lo:[1,0,0] neg_hi:[1,0,0]
	v_mul_f32_e32 v0, v0, v2
	v_cndmask_b32_e32 v0, v4, v0, vcc
	s_waitcnt lgkmcnt(0)
	v_mul_f32_e32 v0, v0, v209
	v_mul_f32_e32 v60, 0x3caaaaab, v0
	ds_write_b32 v62, v60 offset:960
	s_waitcnt vmcnt(0)
	v_cvt_scalef32_pk32_bf16_fp6 v[0:15], v[44:49], 1.0
	v_dot2_f32_bf16 v23, v0, v212, 0
	v_dot2_f32_bf16 v25, v1, v213, 0
	v_dot2_f32_bf16 v22, v2, v214, 0
	v_dot2_f32_bf16 v24, v3, v215, 0
	v_dot2c_f32_bf16_e32 v23, v4, v218
	v_dot2c_f32_bf16_e32 v25, v5, v219
	v_dot2c_f32_bf16_e32 v22, v6, v220
	v_dot2c_f32_bf16_e32 v24, v7, v221
	v_dot2c_f32_bf16_e32 v23, v8, v222
	v_dot2c_f32_bf16_e32 v25, v9, v223
	v_dot2c_f32_bf16_e32 v22, v10, v224
	v_dot2c_f32_bf16_e32 v24, v11, v225
	v_dot2c_f32_bf16_e32 v23, v12, v226
	v_dot2c_f32_bf16_e32 v25, v13, v227
	v_dot2c_f32_bf16_e32 v22, v14, v228
	v_dot2c_f32_bf16_e32 v24, v15, v229
	v_cvt_scalef32_pk32_bf16_fp6 v[0:15], v[50:55], 1.0
	v_dot2c_f32_bf16_e32 v23, v0, v230
	v_dot2c_f32_bf16_e32 v25, v1, v231
	v_dot2c_f32_bf16_e32 v22, v2, v232
	v_dot2c_f32_bf16_e32 v24, v3, v233
	v_dot2c_f32_bf16_e32 v23, v4, v234
	v_dot2c_f32_bf16_e32 v25, v5, v235
	v_dot2c_f32_bf16_e32 v22, v6, v236
	v_dot2c_f32_bf16_e32 v24, v7, v237
	v_dot2c_f32_bf16_e32 v23, v8, v238
	v_dot2c_f32_bf16_e32 v25, v9, v239
	v_dot2c_f32_bf16_e32 v22, v10, v240
	v_dot2c_f32_bf16_e32 v24, v11, v241
	v_dot2c_f32_bf16_e32 v23, v12, v242
	v_dot2c_f32_bf16_e32 v25, v13, v243
	v_dot2c_f32_bf16_e32 v22, v14, v244
	v_dot2c_f32_bf16_e32 v24, v15, v245
	s_nop 2
	v_pk_add_f32 v[0:1], v[24:25], v[22:23]
	s_nop 0
	v_add_f32_e32 v63, v0, v1
	v_add_u32_e32 v62, v61, v155
	ds_read_b32 v211, v62 offset:1984
	v_cndmask_b32_e64 v2, v216, v250, s[58:59]
	v_cndmask_b32_e64 v3, v250, v216, s[58:59]
	v_cndmask_b32_e64 v4, v63, v217, s[58:59]
	v_cndmask_b32_e64 v5, v217, v63, s[58:59]
	v_add_f32_dpp v3, v2, v3 quad_perm:[1,0,3,2] row_mask:0xf bank_mask:0xf bound_ctrl:1
	v_add_f32_dpp v5, v4, v5 quad_perm:[1,0,3,2] row_mask:0xf bank_mask:0xf bound_ctrl:1
	v_cndmask_b32_e64 v2, v5, v3, s[60:61]
	v_cndmask_b32_e64 v0, v3, v5, s[60:61]
	s_nop 0
	v_add_f32_dpp v0, v2, v0 quad_perm:[2,3,0,1] row_mask:0xf bank_mask:0xf bound_ctrl:1
	s_nop 1
	v_add_f32_dpp v0, v0, v0 row_ror:4 row_mask:0xf bank_mask:0xf bound_ctrl:1
	s_nop 1
	v_add_f32_dpp v0, v0, v0 row_ror:8 row_mask:0xf bank_mask:0xf bound_ctrl:1
	v_mul_f32_e32 v0, 0x3caaaaab, v0
	v_and_b32_e32 v2, 0x7fffffff, v0
	v_pk_fma_f32 v[2:3], v[2:3], s[16:17], 1.0 op_sel_hi:[0,0,0]
	v_rcp_f32_e32 v2, v2
	v_rcp_f32_e32 v3, v3
	v_mul_f32_e32 v1, v0, v0
	v_mul_f32_e32 v1, 0xbf38aa3b, v1
	v_cmp_gt_f32_e32 vcc, 0, v0
	v_pk_fma_f32 v[4:5], v[2:3], s[24:25], v[130:131] op_sel_hi:[1,0,0]
	s_nop 0
	v_pk_fma_f32 v[4:5], v[2:3], v[4:5], s[28:29] op_sel_hi:[1,1,0]
	s_nop 0
	v_pk_fma_f32 v[4:5], v[2:3], v[4:5], s[30:31] op_sel_hi:[1,1,0]
	s_nop 0
	v_pk_fma_f32 v[4:5], v[2:3], v[4:5], s[36:37] op_sel_hi:[1,1,0]
	s_nop 0
	v_pk_mul_f32 v[2:3], v[2:3], v[4:5]
	v_exp_f32_e32 v4, v1
	s_nop 0
	v_pk_mul_f32 v[2:3], v[4:5], v[2:3] op_sel_hi:[0,1]
	v_pk_fma_f32 v[4:5], v[0:1], v[2:3], v[0:1] op_sel_hi:[0,1,1] neg_lo:[1,0,0] neg_hi:[1,0,0]
	v_mul_f32_e32 v0, v0, v2
	v_cndmask_b32_e32 v0, v4, v0, vcc
	s_waitcnt lgkmcnt(0)
	v_mul_f32_e32 v0, v0, v211
	v_mul_f32_e32 v60, 0x3caaaaab, v0
	ds_write_b32 v62, v60 offset:2496
	v_mov_b32_e32 v180, 0
	v_mov_b32_e32 v181, 0
	v_mov_b32_e32 v182, 0
	v_mov_b32_e32 v183, 0
	v_mov_b32_e32 v184, 0
	v_mov_b32_e32 v185, 0
	v_mov_b32_e32 v186, 0
	v_mov_b32_e32 v187, 0
	v_mov_b32_e32 v188, 0
	v_mov_b32_e32 v189, 0
	v_mov_b32_e32 v190, 0
	v_mov_b32_e32 v191, 0
	v_mov_b32_e32 v192, 0
	v_mov_b32_e32 v193, 0
	v_mov_b32_e32 v194, 0
	v_mov_b32_e32 v195, 0
	v_mov_b32_e32 v196, 0
	v_mov_b32_e32 v197, 0
	v_mov_b32_e32 v198, 0
	v_mov_b32_e32 v199, 0
	v_mov_b32_e32 v200, 0
	v_mov_b32_e32 v201, 0
	v_mov_b32_e32 v202, 0
	v_mov_b32_e32 v203, 0
	v_mov_b32_e32 v204, 0
	v_mov_b32_e32 v205, 0
	v_mov_b32_e32 v206, 0
	v_mov_b32_e32 v207, 0
	v_mov_b32_e32 v208, 0
	v_mov_b32_e32 v209, 0
	v_mov_b32_e32 v210, 0
	v_mov_b32_e32 v211, 0
	s_barrier
; __device__ void ph_peer(const float* __restrict__ SC, const bf16_t* __restrict__ H  , const float* __restrict__ gffn, const unsigned char* __restrict__ U, const unsigned char* __restrict__ V, float* X, const float* __restrict__ fgain) {
;     ...
;         for (int it = 0; it < 32; ++it) {
;             const int src = (it * 4 + grp) & 63;
;             const int e = __shfl(it < 16 ? idx_lo : idx_hi, src);
;             const float gt = __shfl(it < 16 ? g_lo : g_hi, src);
;             const u32x4* up = (const u32x4*)(U + (size_t)e * 768 + 48 * sub);
;             const u32x4 u0 = up[0], u1 = up[1], u2 = up[2];
;             u32x2 vw[2][3];
; #pragma unroll
;             for (int r = 0; r < 2; ++r) { const int ea = __builtin_amdgcn_readlane(e, 32 * r), eb = __builtin_amdgcn_readlane(e, 32 * r + 16);
;                 const u32x2* vp = (const u32x2*)(V + (size_t)(half ? eb : ea) * 768 + 24 * c32); vw[r][0] = vp[0]; vw[r][1] = vp[1]; vw[r][2] = vp[2]; }
	v_lshrrev_b32_e32 v61, 6, v131
	v_lshrrev_b32_e32 v0, 5, v74
	v_mul_u32_u24_e32 v61, 0x2400, v61
	v_lshl_add_u32 v61, v0, 2, v61
	s_mov_b32 s1, 0
	ds_read_b32 v32, v61 offset:0
	ds_read_b32 v33, v61 offset:8
	ds_read_b32 v56, v61 offset:1024
	ds_read_b32 v58, v61 offset:1032
	v_add_u32_e32 v61, 16, v61
	s_add_i32 s1, s1, 1
	s_waitcnt lgkmcnt(2)
	v_mad_u32_u24 v0, v32, s14, v93
	v_mad_u32_u24 v1, v33, s14, v93
	global_load_dwordx4 v[44:47], v0, s[48:49]
	global_load_dwordx2 v[48:49], v0, s[48:49] offset:16
	global_load_dwordx4 v[50:53], v1, s[48:49]
	global_load_dwordx2 v[54:55], v1, s[48:49] offset:16
